# cross-attention QK^T: K-fragment LDS reads rotated over three register quads with two reads in flight and counted waits (was one quad, lgkmcnt(0) before every MFMA)
# baseline (speedup 1.0000x reference)
; __device__ __forceinline__ float row_rs(const float* ssq, int row) { return ssq ? rsqrtf(ssq[row] * (1.f / 1024.f) + RMS_EPS) : 1.f; }
; #define LAS __attribute__((address_space(3)))
; __device__ __forceinline__ unsigned pk2(float lo, float hi) { return pg8::cvt_pk_bf16(lo, hi); }
;     __device__ __forceinline__ void fused(f32x4 (&acc)[2][2][4][2], const pg8::Unit& u, int wr, int wc, int fr, int fq, LAS unsigned char* lds, int wid, int lane) const {
;         LAS bf16* QI = (LAS bf16*)lds;
; #pragma unroll
;         for (int ai = 0; ai < 2; ++ai)
; #pragma unroll
;             for (int m = 0; m < 4; ++m) { const int rl = ai * 128 + wr * 64 + m * 16 + fr; const float rs = pg8::row_rs(ssq, u.pm * 256 + rl);
; #pragma unroll
;                 for (int bj = 0; bj < 2; ++bj)
; #pragma unroll
;                     for (int n = 0; n < 2; ++n) { const f32x4 v = acc[ai][bj][m][n] * rs; v2u w; w.x = pk2(v[0], v[1]); w.y = pk2(v[2], v[3]);
;                         *(LAS v2u*)(QI + rl * XP + bj * 128 + wc * 32 + n * 16 + 4 * fq) = w; } }
.LBB0_1108:
	s_add_u32 s4, s48, 0x20000
	s_addc_u32 s5, s49, 0
	v_lshrrev_b32_e32 v128, 5, v208
	s_lshl_b32 s13, s10, 8
	v_lshlrev_b32_e32 v189, 4, v128
	v_lshlrev_b32_e32 v211, 2, v128
	v_add_u32_e32 v128, s13, v146
	v_ashrrev_i32_e32 v129, 31, v128
	v_lshl_add_u64 v[132:133], v[128:129], 2, s[4:5]
	s_barrier
	global_load_dword v131, v[132:133], off
	s_lshl_b32 s6, s39, 6
	v_mov_b32_e32 v129, 0x358637bd
	s_add_i32 s7, s6, 0
	s_mov_b32 s6, 0x800000
	s_movk_i32 s14, 0x210
	s_ashr_i32 s15, s10, 4
	s_add_i32 s12, 0, 0x10800
	s_andn2_b32 s30, s30, 63
	v_and_b32_e32 v210, 31, v209
	v_and_b32_e32 v188, 8, v147
	v_and_b32_e32 v190, 0x1f0, v144
	v_lshl_or_b32 v214, s31, 5, v210
	v_mov_b32_e32 v191, 0
	v_lshlrev_b32_e32 v130, 1, v188
	v_add_u32_e32 v216, 0, v190
	v_add_u32_e32 v215, s12, v190
	v_mul_u32_u24_e32 v212, 0x210, v210
	v_add3_u32 v213, 0, v212, v189
	s_mov_b32 s11, 0
	s_waitcnt vmcnt(0)
	v_fmamk_f32 v131, v131, 0x3a800000, v129
	v_cmp_gt_f32_e32 vcc, s6, v131
	v_mul_f32_e32 v132, 0x4b800000, v131
	s_nop 0
	v_cndmask_b32_e32 v131, v131, v132, vcc
	v_rsq_f32_e32 v131, v131
	s_nop 0
	v_mul_f32_e32 v132, 0x45800000, v131
	v_cndmask_b32_e32 v132, v131, v132, vcc
	v_mul_lo_u32 v131, v146, s14
	v_pk_mul_f32 v[118:119], v[118:119], v[132:133] op_sel_hi:[1,0]
	v_pk_mul_f32 v[116:117], v[116:117], v[132:133] op_sel_hi:[1,0]
	v_pk_mul_f32 v[114:115], v[114:115], v[132:133] op_sel_hi:[1,0]
	v_pk_mul_f32 v[112:113], v[112:113], v[132:133] op_sel_hi:[1,0]
	v_add3_u32 v131, s7, v145, v131
	v_cvt_pk_bf16_f32 v116, v116, v117
	v_cvt_pk_bf16_f32 v117, v118, v119
	v_cvt_pk_bf16_f32 v112, v112, v113
	v_cvt_pk_bf16_f32 v113, v114, v115
	ds_write2_b64 v131, v[116:117], v[112:113] offset0:32 offset1:36
	v_add_u32_e32 v112, 16, v128
	v_ashrrev_i32_e32 v113, 31, v112
	v_lshl_add_u64 v[112:113], v[112:113], 2, s[4:5]
	global_load_dword v112, v[112:113], off
	v_pk_mul_f32 v[126:127], v[126:127], v[132:133] op_sel_hi:[1,0]
	v_pk_mul_f32 v[124:125], v[124:125], v[132:133] op_sel_hi:[1,0]
	v_pk_mul_f32 v[122:123], v[122:123], v[132:133] op_sel_hi:[1,0]
	v_pk_mul_f32 v[120:121], v[120:121], v[132:133] op_sel_hi:[1,0]
	v_cvt_pk_bf16_f32 v124, v124, v125
	v_cvt_pk_bf16_f32 v125, v126, v127
	v_cvt_pk_bf16_f32 v120, v120, v121
	v_cvt_pk_bf16_f32 v121, v122, v123
	ds_write2_b64 v131, v[124:125], v[120:121] offset1:4
	s_waitcnt vmcnt(0)
	v_fmamk_f32 v112, v112, 0x3a800000, v129
	v_cmp_gt_f32_e32 vcc, s6, v112
	v_mul_f32_e32 v113, 0x4b800000, v112
	s_nop 0
	v_cndmask_b32_e32 v112, v112, v113, vcc
	v_rsq_f32_e32 v112, v112
	s_nop 0
	v_mul_f32_e32 v113, 0x45800000, v112
	v_cndmask_b32_e32 v112, v112, v113, vcc
	v_add_u32_e32 v113, 0x2100, v131
	v_pk_mul_f32 v[106:107], v[106:107], v[112:113] op_sel_hi:[1,0]
	v_pk_mul_f32 v[104:105], v[104:105], v[112:113] op_sel_hi:[1,0]
	v_pk_mul_f32 v[102:103], v[102:103], v[112:113] op_sel_hi:[1,0]
	v_pk_mul_f32 v[100:101], v[100:101], v[112:113] op_sel_hi:[1,0]
	v_pk_mul_f32 v[98:99], v[98:99], v[112:113] op_sel_hi:[1,0]
	v_pk_mul_f32 v[96:97], v[96:97], v[112:113] op_sel_hi:[1,0]
	v_cvt_pk_bf16_f32 v104, v104, v105
	v_cvt_pk_bf16_f32 v105, v106, v107
	v_add_u32_e32 v106, 0x2000, v131
	v_cvt_pk_bf16_f32 v100, v100, v101
	v_cvt_pk_bf16_f32 v101, v102, v103
	v_cvt_pk_bf16_f32 v96, v96, v97
	v_cvt_pk_bf16_f32 v97, v98, v99
	ds_write2_b64 v106, v[100:101], v[96:97] offset0:64 offset1:68
	v_add_u32_e32 v96, 32, v128
	v_ashrrev_i32_e32 v97, 31, v96
	v_lshl_add_u64 v[96:97], v[96:97], 2, s[4:5]
	global_load_dword v96, v[96:97], off
	v_pk_mul_f32 v[110:111], v[110:111], v[112:113] op_sel_hi:[1,0]
	v_pk_mul_f32 v[108:109], v[108:109], v[112:113] op_sel_hi:[1,0]
	s_waitcnt vmcnt(0)
	v_fmamk_f32 v96, v96, 0x3a800000, v129
	v_cmp_gt_f32_e32 vcc, s6, v96
	v_mul_f32_e32 v97, 0x4b800000, v96
	v_cvt_pk_bf16_f32 v108, v108, v109
	v_cndmask_b32_e32 v96, v96, v97, vcc
	v_rsq_f32_e32 v96, v96
	v_cvt_pk_bf16_f32 v109, v110, v111
	ds_write2_b64 v106, v[108:109], v[104:105] offset0:32 offset1:36
	v_mul_f32_e32 v97, 0x45800000, v96
	v_cndmask_b32_e32 v96, v96, v97, vcc
	v_add_u32_e32 v97, 0x4200, v131
	v_pk_mul_f32 v[90:91], v[90:91], v[96:97] op_sel_hi:[1,0]
	v_pk_mul_f32 v[88:89], v[88:89], v[96:97] op_sel_hi:[1,0]
	v_pk_mul_f32 v[86:87], v[86:87], v[96:97] op_sel_hi:[1,0]
	v_pk_mul_f32 v[84:85], v[84:85], v[96:97] op_sel_hi:[1,0]
	v_pk_mul_f32 v[82:83], v[82:83], v[96:97] op_sel_hi:[1,0]
	v_pk_mul_f32 v[80:81], v[80:81], v[96:97] op_sel_hi:[1,0]
	v_cvt_pk_bf16_f32 v88, v88, v89
	v_cvt_pk_bf16_f32 v89, v90, v91
	v_add_u32_e32 v90, 0x4000, v131
	v_cvt_pk_bf16_f32 v84, v84, v85
	v_cvt_pk_bf16_f32 v85, v86, v87
	v_cvt_pk_bf16_f32 v80, v80, v81
	v_cvt_pk_bf16_f32 v81, v82, v83
	ds_write2_b64 v90, v[84:85], v[80:81] offset0:96 offset1:100
	v_add_u32_e32 v80, 48, v128
	v_ashrrev_i32_e32 v81, 31, v80
	v_lshl_add_u64 v[80:81], v[80:81], 2, s[4:5]
	global_load_dword v80, v[80:81], off
	v_pk_mul_f32 v[94:95], v[94:95], v[96:97] op_sel_hi:[1,0]
	v_pk_mul_f32 v[92:93], v[92:93], v[96:97] op_sel_hi:[1,0]
	s_waitcnt vmcnt(0)
; __device__ __forceinline__ float row_rs(const float* ssq, int row) { return ssq ? rsqrtf(ssq[row] * (1.f / 1024.f) + RMS_EPS) : 1.f; }
; #define LAS __attribute__((address_space(3)))
; __device__ __forceinline__ unsigned pk2(float lo, float hi) { return pg8::cvt_pk_bf16(lo, hi); }
;     __device__ __forceinline__ void fused(f32x4 (&acc)[2][2][4][2], const pg8::Unit& u, int wr, int wc, int fr, int fq, LAS unsigned char* lds, int wid, int lane) const {
;     ...
;             for (int m = 0; m < 4; ++m) { const int rl = ai * 128 + wr * 64 + m * 16 + fr; const float rs = pg8::row_rs(ssq, u.pm * 256 + rl);
; #pragma unroll
;                 for (int bj = 0; bj < 2; ++bj)
; #pragma unroll
;                     for (int n = 0; n < 2; ++n) { const f32x4 v = acc[ai][bj][m][n] * rs; v2u w; w.x = pk2(v[0], v[1]); w.y = pk2(v[2], v[3]);
;                         *(LAS v2u*)(QI + rl * XP + bj * 128 + wc * 32 + n * 16 + 4 * fq) = w; } }
	v_fmamk_f32 v80, v80, 0x3a800000, v129
	v_cmp_gt_f32_e32 vcc, s6, v80
	v_mul_f32_e32 v81, 0x4b800000, v80
	v_cvt_pk_bf16_f32 v92, v92, v93
	v_cndmask_b32_e32 v80, v80, v81, vcc
	v_rsq_f32_e32 v80, v80
	v_cvt_pk_bf16_f32 v93, v94, v95
	ds_write2_b64 v90, v[92:93], v[88:89] offset0:64 offset1:68
	v_mul_f32_e32 v81, 0x45800000, v80
	v_cndmask_b32_e32 v82, v80, v81, vcc
	v_pk_mul_f32 v[74:75], v[74:75], v[82:83] op_sel_hi:[1,0]
	v_pk_mul_f32 v[72:73], v[72:73], v[82:83] op_sel_hi:[1,0]
	v_pk_mul_f32 v[70:71], v[70:71], v[82:83] op_sel_hi:[1,0]
	v_pk_mul_f32 v[68:69], v[68:69], v[82:83] op_sel_hi:[1,0]
	v_pk_mul_f32 v[66:67], v[66:67], v[82:83] op_sel_hi:[1,0]
	v_pk_mul_f32 v[64:65], v[64:65], v[82:83] op_sel_hi:[1,0]
	v_cvt_pk_bf16_f32 v72, v72, v73
	v_cvt_pk_bf16_f32 v73, v74, v75
	v_add_u32_e32 v74, 0x6000, v131
	v_cvt_pk_bf16_f32 v68, v68, v69
	v_cvt_pk_bf16_f32 v69, v70, v71
	v_cvt_pk_bf16_f32 v64, v64, v65
	v_cvt_pk_bf16_f32 v65, v66, v67
	ds_write2_b64 v74, v[68:69], v[64:65] offset0:128 offset1:132
	v_add_u32_e32 v64, 0x80, v128
	v_ashrrev_i32_e32 v65, 31, v64
	v_lshl_add_u64 v[64:65], v[64:65], 2, s[4:5]
	global_load_dword v64, v[64:65], off
	v_add_u32_e32 v80, 0x6300, v131
	v_pk_mul_f32 v[78:79], v[78:79], v[82:83] op_sel_hi:[1,0]
	v_pk_mul_f32 v[76:77], v[76:77], v[82:83] op_sel_hi:[1,0]
	v_add3_u32 v68, s12, v212, v189
	v_cvt_pk_bf16_f32 v76, v76, v77
	v_cvt_pk_bf16_f32 v77, v78, v79
	ds_write2_b64 v74, v[76:77], v[72:73] offset0:96 offset1:100
	v_add3_u32 v189, s12, v189, v212
	s_waitcnt vmcnt(0)
	v_fmamk_f32 v64, v64, 0x3a800000, v129
	v_cmp_gt_f32_e32 vcc, s6, v64
	v_mul_f32_e32 v65, 0x4b800000, v64
	s_nop 0
	v_cndmask_b32_e32 v64, v64, v65, vcc
	v_rsq_f32_e32 v64, v64
	s_nop 0
	v_mul_f32_e32 v65, 0x45800000, v64
	v_cndmask_b32_e32 v66, v64, v65, vcc
	v_pk_mul_f32 v[54:55], v[54:55], v[66:67] op_sel_hi:[1,0]
	v_pk_mul_f32 v[52:53], v[52:53], v[66:67] op_sel_hi:[1,0]
	v_pk_mul_f32 v[50:51], v[50:51], v[66:67] op_sel_hi:[1,0]
	v_pk_mul_f32 v[48:49], v[48:49], v[66:67] op_sel_hi:[1,0]
	v_cvt_pk_bf16_f32 v52, v52, v53
	v_cvt_pk_bf16_f32 v53, v54, v55
	v_cvt_pk_bf16_f32 v48, v48, v49
	v_cvt_pk_bf16_f32 v49, v50, v51
	v_add_u32_e32 v50, 0xe800, v113
	ds_write2_b64 v50, v[52:53], v[48:49] offset1:4
	v_add_u32_e32 v48, 0x90, v128
	v_ashrrev_i32_e32 v49, 31, v48
	v_lshl_add_u64 v[48:49], v[48:49], 2, s[4:5]
	global_load_dword v48, v[48:49], off
	v_pk_mul_f32 v[62:63], v[62:63], v[66:67] op_sel_hi:[1,0]
	v_pk_mul_f32 v[60:61], v[60:61], v[66:67] op_sel_hi:[1,0]
	v_pk_mul_f32 v[58:59], v[58:59], v[66:67] op_sel_hi:[1,0]
	v_pk_mul_f32 v[56:57], v[56:57], v[66:67] op_sel_hi:[1,0]
	v_cvt_pk_bf16_f32 v60, v60, v61
	v_cvt_pk_bf16_f32 v61, v62, v63
	v_cvt_pk_bf16_f32 v56, v56, v57
	v_cvt_pk_bf16_f32 v57, v58, v59
	v_add_u32_e32 v58, 0xe000, v113
	ds_write2_b64 v58, v[60:61], v[56:57] offset0:224 offset1:228
	v_add_u32_e32 v64, 0xe700, v113
	s_waitcnt vmcnt(0)
	v_fmamk_f32 v48, v48, 0x3a800000, v129
	v_cmp_gt_f32_e32 vcc, s6, v48
	v_mul_f32_e32 v49, 0x4b800000, v48
	s_nop 0
	v_cndmask_b32_e32 v48, v48, v49, vcc
	v_rsq_f32_e32 v48, v48
	s_nop 0
	v_mul_f32_e32 v49, 0x45800000, v48
	v_cndmask_b32_e32 v48, v48, v49, vcc
	v_pk_mul_f32 v[38:39], v[38:39], v[48:49] op_sel_hi:[1,0]
	v_pk_mul_f32 v[36:37], v[36:37], v[48:49] op_sel_hi:[1,0]
	v_pk_mul_f32 v[34:35], v[34:35], v[48:49] op_sel_hi:[1,0]
	v_pk_mul_f32 v[32:33], v[32:33], v[48:49] op_sel_hi:[1,0]
	v_cvt_pk_bf16_f32 v36, v36, v37
	v_cvt_pk_bf16_f32 v37, v38, v39
	v_cvt_pk_bf16_f32 v32, v32, v33
	v_cvt_pk_bf16_f32 v33, v34, v35
	v_add_u32_e32 v34, 0xe800, v97
	ds_write2_b64 v34, v[36:37], v[32:33] offset1:4
	v_add_u32_e32 v32, 0xa0, v128
	v_ashrrev_i32_e32 v33, 31, v32
	v_lshl_add_u64 v[32:33], v[32:33], 2, s[4:5]
	global_load_dword v32, v[32:33], off
	v_pk_mul_f32 v[46:47], v[46:47], v[48:49] op_sel_hi:[1,0]
	v_pk_mul_f32 v[44:45], v[44:45], v[48:49] op_sel_hi:[1,0]
	v_pk_mul_f32 v[42:43], v[42:43], v[48:49] op_sel_hi:[1,0]
	v_pk_mul_f32 v[40:41], v[40:41], v[48:49] op_sel_hi:[1,0]
	v_cvt_pk_bf16_f32 v44, v44, v45
	v_cvt_pk_bf16_f32 v45, v46, v47
	v_cvt_pk_bf16_f32 v40, v40, v41
	v_cvt_pk_bf16_f32 v41, v42, v43
	v_add_u32_e32 v42, 0xe000, v97
	ds_write2_b64 v42, v[44:45], v[40:41] offset0:224 offset1:228
	s_waitcnt vmcnt(0)
	v_fmamk_f32 v32, v32, 0x3a800000, v129
	v_cmp_gt_f32_e32 vcc, s6, v32
	v_mul_f32_e32 v33, 0x4b800000, v32
	s_nop 0
	v_cndmask_b32_e32 v32, v32, v33, vcc
	v_rsq_f32_e32 v32, v32
	s_nop 0
	v_mul_f32_e32 v33, 0x45800000, v32
	v_cndmask_b32_e32 v32, v32, v33, vcc
	v_pk_mul_f32 v[22:23], v[22:23], v[32:33] op_sel_hi:[1,0]
	v_pk_mul_f32 v[20:21], v[20:21], v[32:33] op_sel_hi:[1,0]
	v_pk_mul_f32 v[18:19], v[18:19], v[32:33] op_sel_hi:[1,0]
	v_pk_mul_f32 v[16:17], v[16:17], v[32:33] op_sel_hi:[1,0]
	v_cvt_pk_bf16_f32 v20, v20, v21
	v_cvt_pk_bf16_f32 v21, v22, v23
	v_cvt_pk_bf16_f32 v16, v16, v17
	v_cvt_pk_bf16_f32 v17, v18, v19
	v_add_u32_e32 v18, 0xe800, v80
	ds_write2_b64 v18, v[20:21], v[16:17] offset1:4
	v_add_u32_e32 v16, 0xb0, v128
	v_ashrrev_i32_e32 v17, 31, v16
	v_lshl_add_u64 v[16:17], v[16:17], 2, s[4:5]
	global_load_dword v16, v[16:17], off
	v_pk_mul_f32 v[30:31], v[30:31], v[32:33] op_sel_hi:[1,0]
	v_pk_mul_f32 v[28:29], v[28:29], v[32:33] op_sel_hi:[1,0]
	v_pk_mul_f32 v[26:27], v[26:27], v[32:33] op_sel_hi:[1,0]
	v_pk_mul_f32 v[24:25], v[24:25], v[32:33] op_sel_hi:[1,0]
	v_cvt_pk_bf16_f32 v28, v28, v29
	v_cvt_pk_bf16_f32 v29, v30, v31
	v_cvt_pk_bf16_f32 v24, v24, v25
	v_cvt_pk_bf16_f32 v25, v26, v27
	v_add_u32_e32 v26, 0xe000, v80
	v_or_b32_e32 v30, s30, v208
	ds_write2_b64 v26, v[28:29], v[24:25] offset0:224 offset1:228
	v_ashrrev_i32_e32 v34, 5, v30
	v_add_u32_e32 v20, 0xa00, v30
	v_add_u32_e32 v24, 0xc00, v30
	v_ashrrev_i32_e32 v44, 5, v20
	v_ashrrev_i32_e32 v46, 5, v24
	v_ashrrev_i32_e32 v35, 31, v34
	v_ashrrev_i32_e32 v45, 31, v44
	v_ashrrev_i32_e32 v47, 31, v46
	v_lshlrev_b64 v[192:193], 11, v[34:35]
	v_lshlrev_b64 v[202:203], 11, v[44:45]
	v_lshlrev_b64 v[204:205], 11, v[46:47]
	v_mul_lo_u32 v34, v34, s14
	v_add_u32_e32 v223, v216, v34
	v_add_u32_e32 v230, v215, v34
	s_waitcnt vmcnt(0)
; #define LAS __attribute__((address_space(3)))
; __device__ __forceinline__ unsigned pk2(float lo, float hi) { return pg8::cvt_pk_bf16(lo, hi); }
; __device__ __forceinline__ void stage_half(const bf16* g, LAS bf16* dst, int tid) {
;     v4u t[8];
; #pragma unroll
;     for (int i = 0; i < 8; ++i) { const int ch = tid + i * NT, r = ch >> 5, cc = ch & 31; t[i] = *(const v4u*)(g + (size_t)r * 1024 + cc * 8); }
; #pragma unroll
;     for (int i = 0; i < 8; ++i) { const int ch = tid + i * NT, r = ch >> 5, cc = ch & 31; *(LAS v4u*)(dst + r * XP + cc * 8) = t[i]; }
; }
; __device__ __forceinline__ void xattn_core(unsigned char* ws, LAS unsigned char* lds, int b, int hd, int qb, int tid, const bf16x8 (&qf)[16]) {
;     const int lane = tid & 63, wave = tid >> 6, r32 = lane & 31, hh = lane >> 5;
;     LAS bf16* L0 = (LAS bf16*)lds; LAS bf16* L1 = L0 + 128 * XP;
;     const bf16* Kg = (const bf16*)(ws + WS_KB) + (size_t)(b * 256) * 1024 + hd * 256;
;     const bf16* Vg = (const bf16*)(ws + WS_VT) + (size_t)(hd * 256) * 1024 + b * 256;
;     stage_half(Kg, L0, tid); stage_half(Kg + (size_t)128 * 1024, L1, tid);
;     const int q0 = b * SEQ + qb * 256 + 32 * wave;
;     __syncthreads();
;     __device__ __forceinline__ void fused(f32x4 (&acc)[2][2][4][2], const pg8::Unit& u, int wr, int wc, int fr, int fq, LAS unsigned char* lds, int wid, int lane) const {
;     ...
;                     for (int n = 0; n < 2; ++n) { const f32x4 v = acc[ai][bj][m][n] * rs; v2u w; w.x = pk2(v[0], v[1]); w.y = pk2(v[2], v[3]);
;                         *(LAS v2u*)(QI + rl * XP + bj * 128 + wc * 32 + n * 16 + 4 * fq) = w; } }
;         __syncthreads();
;         const int r32 = lane & 31, hh = lane >> 5; bf16x8 qf[16];
; #pragma unroll
;         for (int ds = 0; ds < 16; ++ds) qf[ds] = *(const LAS bf16x8*)(QI + (32 * wid + r32) * XP + 16 * ds + 8 * hh);
	v_fmac_f32_e32 v129, 0x3a800000, v16
	v_cmp_gt_f32_e32 vcc, s6, v129
	v_mul_f32_e32 v16, 0x4b800000, v129
	s_lshl_b32 s6, s15, 8
	v_cndmask_b32_e32 v16, v129, v16, vcc
	v_rsq_f32_e32 v16, v16
	s_ashr_i32 s7, s6, 31
	s_lshl_b64 s[4:5], s[6:7], 11
	s_add_u32 s10, s48, s4
	v_mul_f32_e32 v17, 0x45800000, v16
	v_cndmask_b32_e32 v16, v16, v17, vcc
	s_addc_u32 s19, s49, s5
	s_lshl_b32 s16, s34, 8
	v_pk_mul_f32 v[14:15], v[14:15], v[16:17] op_sel_hi:[1,0]
	v_pk_mul_f32 v[12:13], v[12:13], v[16:17] op_sel_hi:[1,0]
	v_pk_mul_f32 v[10:11], v[10:11], v[16:17] op_sel_hi:[1,0]
	v_pk_mul_f32 v[8:9], v[8:9], v[16:17] op_sel_hi:[1,0]
	v_pk_mul_f32 v[6:7], v[6:7], v[16:17] op_sel_hi:[1,0]
	v_pk_mul_f32 v[4:5], v[4:5], v[16:17] op_sel_hi:[1,0]
	v_pk_mul_f32 v[2:3], v[2:3], v[16:17] op_sel_hi:[1,0]
	v_pk_mul_f32 v[0:1], v[0:1], v[16:17] op_sel_hi:[1,0]
	s_ashr_i32 s17, s16, 31
	v_cvt_pk_bf16_f32 v12, v12, v13
	v_cvt_pk_bf16_f32 v13, v14, v15
	v_cvt_pk_bf16_f32 v8, v8, v9
	v_cvt_pk_bf16_f32 v9, v10, v11
	v_add_u32_e32 v10, 0x6000, v64
	v_cvt_pk_bf16_f32 v4, v4, v5
	v_cvt_pk_bf16_f32 v5, v6, v7
	v_cvt_pk_bf16_f32 v0, v0, v1
	v_cvt_pk_bf16_f32 v1, v2, v3
	s_lshl_b64 s[4:5], s[16:17], 1
	ds_write2_b64 v10, v[12:13], v[8:9] offset0:96 offset1:100
	ds_write2_b64 v10, v[4:5], v[0:1] offset0:128 offset1:132
	s_add_u32 s18, s10, s4
	v_add_u32_e32 v4, 0x200, v30
	v_add_u32_e32 v8, 0x400, v30
	v_add_u32_e32 v12, 0x600, v30
	v_add_u32_e32 v16, 0x800, v30
	v_add_u32_e32 v30, 0xe00, v30
	s_addc_u32 s19, s19, s5
	v_ashrrev_i32_e32 v36, 5, v4
	v_ashrrev_i32_e32 v38, 5, v8
	v_ashrrev_i32_e32 v40, 5, v12
	v_ashrrev_i32_e32 v42, 5, v16
	v_ashrrev_i32_e32 v48, 5, v30
	v_mul_lo_u32 v0, v214, s14
	v_lshl_add_u64 v[32:33], s[18:19], 0, v[190:191]
	s_mov_b64 s[18:19], 0x5600000
	v_ashrrev_i32_e32 v37, 31, v36
	v_ashrrev_i32_e32 v39, 31, v38
	v_ashrrev_i32_e32 v41, 31, v40
	v_ashrrev_i32_e32 v43, 31, v42
	v_ashrrev_i32_e32 v49, 31, v48
	v_add3_u32 v0, 0, v130, v0
	v_lshl_add_u64 v[28:29], v[32:33], 0, s[18:19]
	v_lshlrev_b64 v[194:195], 11, v[36:37]
	v_lshlrev_b64 v[196:197], 11, v[38:39]
	v_lshlrev_b64 v[198:199], 11, v[40:41]
	v_lshlrev_b64 v[200:201], 11, v[42:43]
	v_lshlrev_b64 v[206:207], 11, v[48:49]
	s_waitcnt lgkmcnt(0)
	s_barrier
	ds_read_b128 v[112:115], v0
	ds_read_b128 v[184:187], v0 offset:32
	ds_read_b128 v[180:183], v0 offset:64
	ds_read_b128 v[176:179], v0 offset:96
	ds_read_b128 v[172:175], v0 offset:128
	ds_read_b128 v[168:171], v0 offset:160
	ds_read_b128 v[164:167], v0 offset:192
	ds_read_b128 v[160:163], v0 offset:224
	ds_read_b128 v[156:159], v0 offset:256
	ds_read_b128 v[152:155], v0 offset:288
	ds_read_b128 v[148:151], v0 offset:320
	ds_read_b128 v[144:147], v0 offset:352
	ds_read_b128 v[140:143], v0 offset:384
	ds_read_b128 v[136:139], v0 offset:416
	ds_read_b128 v[132:135], v0 offset:448
	ds_read_b128 v[128:131], v0 offset:480
	v_lshl_add_u64 v[0:1], v[28:29], 0, v[192:193]
	v_lshl_add_u64 v[4:5], v[28:29], 0, v[194:195]
	v_lshl_add_u64 v[8:9], v[28:29], 0, v[196:197]
	v_lshl_add_u64 v[12:13], v[28:29], 0, v[198:199]
	v_lshl_add_u64 v[16:17], v[28:29], 0, v[200:201]
	v_lshl_add_u64 v[20:21], v[28:29], 0, v[202:203]
	v_lshl_add_u64 v[24:25], v[28:29], 0, v[204:205]
	v_lshl_add_u64 v[28:29], v[28:29], 0, v[206:207]
	s_waitcnt lgkmcnt(0)
	s_barrier
	global_load_dwordx4 v[0:3], v[0:1], off
	v_mul_lo_u32 v35, v36, s14
	global_load_dwordx4 v[4:7], v[4:5], off
	v_mul_lo_u32 v36, v38, s14
	global_load_dwordx4 v[8:11], v[8:9], off
	v_mul_lo_u32 v37, v40, s14
	global_load_dwordx4 v[12:15], v[12:13], off
	v_mul_lo_u32 v38, v42, s14
	global_load_dwordx4 v[16:19], v[16:17], off
	v_mul_lo_u32 v39, v44, s14
	global_load_dwordx4 v[20:23], v[20:21], off
	v_mul_lo_u32 v40, v46, s14
	global_load_dwordx4 v[24:27], v[24:25], off
	v_mul_lo_u32 v41, v48, s14
	global_load_dwordx4 v[28:31], v[28:29], off
	v_add_u32_e32 v222, v216, v35
	v_add_u32_e32 v221, v216, v36
	v_add_u32_e32 v220, v216, v37
	v_add_u32_e32 v219, v216, v38
	v_add_u32_e32 v218, v216, v39
	v_add_u32_e32 v217, v216, v40
	v_add_u32_e32 v216, v216, v41
	s_mov_b64 s[18:19], 0x5640000
	v_add_u32_e32 v224, v215, v35
	v_add_u32_e32 v225, v215, v36
	v_add_u32_e32 v226, v215, v37
	v_add_u32_e32 v227, v215, v38
	v_add_u32_e32 v228, v215, v39
	v_add_u32_e32 v229, v215, v40
	v_add_u32_e32 v215, v215, v41
	s_lshl_b64 s[16:17], s[16:17], 11
	s_add_u32 s16, s48, s16
	s_addc_u32 s17, s49, s17
	s_and_b32 s10, s13, 0xf00
	s_lshl_b64 s[6:7], s[6:7], 1
	s_add_u32 s16, s16, s6
	s_addc_u32 s17, s17, s7
	s_lshl_b32 s6, s15, 12
	s_mov_b64 s[14:15], 0x5800000
	s_mov_b32 s7, 0xff61b1e6
	s_or_b32 s6, s10, s6
	s_waitcnt vmcnt(7)
	ds_write_b128 v223, v[0:3]
	s_waitcnt vmcnt(6)
	ds_write_b128 v222, v[4:7]
	s_waitcnt vmcnt(5)
	ds_write_b128 v221, v[8:11]
	s_waitcnt vmcnt(4)
	ds_write_b128 v220, v[12:15]
	s_waitcnt vmcnt(3)
	ds_write_b128 v219, v[16:19]
	s_waitcnt vmcnt(2)
	ds_write_b128 v218, v[20:23]
	s_waitcnt vmcnt(1)
	ds_write_b128 v217, v[24:27]
	s_waitcnt vmcnt(0)
	ds_write_b128 v216, v[28:31]
	v_lshl_add_u64 v[28:29], v[32:33], 0, s[18:19]
	v_lshl_add_u64 v[0:1], v[28:29], 0, v[192:193]
	v_lshl_add_u64 v[4:5], v[28:29], 0, v[194:195]
	v_lshl_add_u64 v[8:9], v[28:29], 0, v[196:197]
	v_lshl_add_u64 v[12:13], v[28:29], 0, v[198:199]
	v_lshl_add_u64 v[16:17], v[28:29], 0, v[200:201]
	v_lshl_add_u64 v[20:21], v[28:29], 0, v[202:203]
	v_lshl_add_u64 v[24:25], v[28:29], 0, v[204:205]
	v_lshl_add_u64 v[28:29], v[28:29], 0, v[206:207]
	global_load_dwordx4 v[0:3], v[0:1], off
	s_nop 0
	global_load_dwordx4 v[4:7], v[4:5], off
	s_waitcnt vmcnt(1)
	ds_write_b128 v230, v[0:3]
	global_load_dwordx4 v[8:11], v[8:9], off
	s_waitcnt vmcnt(1)
	ds_write_b128 v224, v[4:7]
	global_load_dwordx4 v[12:15], v[12:13], off
	s_waitcnt vmcnt(1)
	ds_write_b128 v225, v[8:11]
	global_load_dwordx4 v[16:19], v[16:17], off
	s_waitcnt vmcnt(1)
	ds_write_b128 v226, v[12:15]
	global_load_dwordx4 v[20:23], v[20:21], off
	s_waitcnt vmcnt(1)
	ds_write_b128 v227, v[16:19]
	global_load_dwordx4 v[24:27], v[24:25], off
	s_waitcnt vmcnt(1)
	ds_write_b128 v228, v[20:23]
	global_load_dwordx4 v[28:31], v[28:29], off
	s_waitcnt vmcnt(1)
	ds_write_b128 v229, v[24:27]
	s_waitcnt vmcnt(0)
	ds_write_b128 v215, v[28:31]
	s_waitcnt lgkmcnt(0)
	s_barrier
; #define LAS __attribute__((address_space(3)))
; __device__ __forceinline__ void xattn_core(unsigned char* ws, LAS unsigned char* lds, int b, int hd, int qb, int tid, const bf16x8 (&qf)[16]) {
;     ...
;     f32x16 sacc[8];
; #pragma unroll
;     for (int mt = 0; mt < 8; ++mt) {
; #pragma unroll
;         for (int r = 0; r < 16; ++r) sacc[mt][r] = 0.f;
;         const LAS bf16* kp = (mt < 4 ? L0 : L1) + ((mt & 3) * 32 + r32) * XP + 8 * hh;
; #pragma unroll
;         for (int ds = 0; ds < 16; ++ds) { const bf16x8 kf = *(const LAS bf16x8*)(kp + 16 * ds); sacc[mt] = __builtin_amdgcn_mfma_f32_32x32x16_bf16(kf, qf[ds], sacc[mt], 0, 0, 0); } }
	ds_read_b128 v[236:239], v213
	ds_read_b128 v[240:243], v213 offset:32
	ds_read_b128 v[244:247], v213 offset:64
	s_waitcnt lgkmcnt(2)
	v_mfma_f32_32x32x16_bf16 v[96:111], v[236:239], v[112:115], 0
	ds_read_b128 v[236:239], v213 offset:96
	s_waitcnt lgkmcnt(2)
	v_mfma_f32_32x32x16_bf16 v[96:111], v[240:243], v[184:187], v[96:111]
	ds_read_b128 v[240:243], v213 offset:128
	s_waitcnt lgkmcnt(2)
	v_mfma_f32_32x32x16_bf16 v[96:111], v[244:247], v[180:183], v[96:111]
	ds_read_b128 v[244:247], v213 offset:160
	s_waitcnt lgkmcnt(2)
	v_mfma_f32_32x32x16_bf16 v[96:111], v[236:239], v[176:179], v[96:111]
	ds_read_b128 v[236:239], v213 offset:192
	s_waitcnt lgkmcnt(2)
	v_mfma_f32_32x32x16_bf16 v[96:111], v[240:243], v[172:175], v[96:111]
	ds_read_b128 v[240:243], v213 offset:224
	s_waitcnt lgkmcnt(2)
	v_mfma_f32_32x32x16_bf16 v[96:111], v[244:247], v[168:171], v[96:111]
	ds_read_b128 v[244:247], v213 offset:256
	s_waitcnt lgkmcnt(2)
	v_mfma_f32_32x32x16_bf16 v[96:111], v[236:239], v[164:167], v[96:111]
	ds_read_b128 v[236:239], v213 offset:288
	s_waitcnt lgkmcnt(2)
	v_mfma_f32_32x32x16_bf16 v[96:111], v[240:243], v[160:163], v[96:111]
	ds_read_b128 v[240:243], v213 offset:320
	s_waitcnt lgkmcnt(2)
	v_mfma_f32_32x32x16_bf16 v[96:111], v[244:247], v[156:159], v[96:111]
	ds_read_b128 v[244:247], v213 offset:352
	s_waitcnt lgkmcnt(2)
	v_mfma_f32_32x32x16_bf16 v[96:111], v[236:239], v[152:155], v[96:111]
	ds_read_b128 v[236:239], v213 offset:384
	s_waitcnt lgkmcnt(2)
	v_mfma_f32_32x32x16_bf16 v[96:111], v[240:243], v[148:151], v[96:111]
	ds_read_b128 v[240:243], v213 offset:416
	s_waitcnt lgkmcnt(2)
	v_mfma_f32_32x32x16_bf16 v[96:111], v[244:247], v[144:147], v[96:111]
	ds_read_b128 v[244:247], v213 offset:448
	s_waitcnt lgkmcnt(2)
	v_mfma_f32_32x32x16_bf16 v[96:111], v[236:239], v[140:143], v[96:111]
	ds_read_b128 v[236:239], v213 offset:480
	s_waitcnt lgkmcnt(2)
	v_mfma_f32_32x32x16_bf16 v[96:111], v[240:243], v[136:139], v[96:111]
	ds_read_b128 v[240:243], v213 offset:16896
	s_waitcnt lgkmcnt(2)
	v_mfma_f32_32x32x16_bf16 v[96:111], v[244:247], v[132:135], v[96:111]
	ds_read_b128 v[244:247], v213 offset:16928
	s_waitcnt lgkmcnt(2)
	v_mfma_f32_32x32x16_bf16 v[96:111], v[236:239], v[128:131], v[96:111]
	ds_read_b128 v[236:239], v213 offset:16960
	s_waitcnt lgkmcnt(2)
	v_mfma_f32_32x32x16_bf16 v[32:47], v[240:243], v[112:115], 0
	ds_read_b128 v[240:243], v213 offset:16992
	s_waitcnt lgkmcnt(2)
	v_mfma_f32_32x32x16_bf16 v[32:47], v[244:247], v[184:187], v[32:47]
	ds_read_b128 v[244:247], v213 offset:17024
	s_waitcnt lgkmcnt(2)
	v_mfma_f32_32x32x16_bf16 v[32:47], v[236:239], v[180:183], v[32:47]
	ds_read_b128 v[236:239], v213 offset:17056
	s_waitcnt lgkmcnt(2)
	v_mfma_f32_32x32x16_bf16 v[32:47], v[240:243], v[176:179], v[32:47]
	ds_read_b128 v[240:243], v213 offset:17088
	s_waitcnt lgkmcnt(2)
	v_mfma_f32_32x32x16_bf16 v[32:47], v[244:247], v[172:175], v[32:47]
	ds_read_b128 v[244:247], v213 offset:17120
	s_waitcnt lgkmcnt(2)
	v_mfma_f32_32x32x16_bf16 v[32:47], v[236:239], v[168:171], v[32:47]
	ds_read_b128 v[236:239], v213 offset:17152
	s_waitcnt lgkmcnt(2)
	v_mfma_f32_32x32x16_bf16 v[32:47], v[240:243], v[164:167], v[32:47]
	ds_read_b128 v[240:243], v213 offset:17184
	s_waitcnt lgkmcnt(2)
	v_mfma_f32_32x32x16_bf16 v[32:47], v[244:247], v[160:163], v[32:47]
	ds_read_b128 v[244:247], v213 offset:17216
	s_waitcnt lgkmcnt(2)
	v_mfma_f32_32x32x16_bf16 v[32:47], v[236:239], v[156:159], v[32:47]
	ds_read_b128 v[236:239], v213 offset:17248
	s_waitcnt lgkmcnt(2)
	v_mfma_f32_32x32x16_bf16 v[32:47], v[240:243], v[152:155], v[32:47]
	ds_read_b128 v[240:243], v213 offset:17280
	s_waitcnt lgkmcnt(2)
	v_mfma_f32_32x32x16_bf16 v[32:47], v[244:247], v[148:151], v[32:47]
	ds_read_b128 v[244:247], v213 offset:17312
	s_waitcnt lgkmcnt(2)
	v_mfma_f32_32x32x16_bf16 v[32:47], v[236:239], v[144:147], v[32:47]
	ds_read_b128 v[236:239], v213 offset:17344
	s_waitcnt lgkmcnt(2)
	v_mfma_f32_32x32x16_bf16 v[32:47], v[240:243], v[140:143], v[32:47]
	ds_read_b128 v[240:243], v213 offset:17376
	s_waitcnt lgkmcnt(2)
	v_mfma_f32_32x32x16_bf16 v[32:47], v[244:247], v[136:139], v[32:47]
	ds_read_b128 v[244:247], v213 offset:33792
	s_waitcnt lgkmcnt(2)
	v_mfma_f32_32x32x16_bf16 v[32:47], v[236:239], v[132:135], v[32:47]
	ds_read_b128 v[236:239], v213 offset:33824
	s_waitcnt lgkmcnt(2)
	v_mfma_f32_32x32x16_bf16 v[32:47], v[240:243], v[128:131], v[32:47]
	ds_read_b128 v[240:243], v213 offset:33856
	s_waitcnt lgkmcnt(2)
	v_mfma_f32_32x32x16_bf16 v[16:31], v[244:247], v[112:115], 0
	ds_read_b128 v[244:247], v213 offset:33888
	s_waitcnt lgkmcnt(2)
	v_mfma_f32_32x32x16_bf16 v[16:31], v[236:239], v[184:187], v[16:31]
	ds_read_b128 v[236:239], v213 offset:33920
	s_waitcnt lgkmcnt(2)
	v_mfma_f32_32x32x16_bf16 v[16:31], v[240:243], v[180:183], v[16:31]
	ds_read_b128 v[240:243], v213 offset:33952
	s_waitcnt lgkmcnt(2)
	v_mfma_f32_32x32x16_bf16 v[16:31], v[244:247], v[176:179], v[16:31]
	ds_read_b128 v[244:247], v213 offset:33984
	s_waitcnt lgkmcnt(2)
	v_mfma_f32_32x32x16_bf16 v[16:31], v[236:239], v[172:175], v[16:31]
	ds_read_b128 v[236:239], v213 offset:34016
	s_waitcnt lgkmcnt(2)
	v_mfma_f32_32x32x16_bf16 v[16:31], v[240:243], v[168:171], v[16:31]
	ds_read_b128 v[240:243], v213 offset:34048
	s_waitcnt lgkmcnt(2)
	v_mfma_f32_32x32x16_bf16 v[16:31], v[244:247], v[164:167], v[16:31]
	ds_read_b128 v[244:247], v213 offset:34080
	s_waitcnt lgkmcnt(2)
	v_mfma_f32_32x32x16_bf16 v[16:31], v[236:239], v[160:163], v[16:31]
	ds_read_b128 v[236:239], v213 offset:34112
	s_waitcnt lgkmcnt(2)
	v_mfma_f32_32x32x16_bf16 v[16:31], v[240:243], v[156:159], v[16:31]
	ds_read_b128 v[240:243], v213 offset:34144
	s_waitcnt lgkmcnt(2)
; #define LAS __attribute__((address_space(3)))
; __device__ __forceinline__ void xattn_core(unsigned char* ws, LAS unsigned char* lds, int b, int hd, int qb, int tid, const bf16x8 (&qf)[16]) {
;     ...
;     f32x16 sacc[8];
; #pragma unroll
;     for (int mt = 0; mt < 8; ++mt) {
; #pragma unroll
;         for (int r = 0; r < 16; ++r) sacc[mt][r] = 0.f;
;         const LAS bf16* kp = (mt < 4 ? L0 : L1) + ((mt & 3) * 32 + r32) * XP + 8 * hh;
; #pragma unroll
;         for (int ds = 0; ds < 16; ++ds) { const bf16x8 kf = *(const LAS bf16x8*)(kp + 16 * ds); sacc[mt] = __builtin_amdgcn_mfma_f32_32x32x16_bf16(kf, qf[ds], sacc[mt], 0, 0, 0); } }
	v_mfma_f32_32x32x16_bf16 v[16:31], v[244:247], v[152:155], v[16:31]
	ds_read_b128 v[244:247], v213 offset:34176
	s_waitcnt lgkmcnt(2)
	v_mfma_f32_32x32x16_bf16 v[16:31], v[236:239], v[148:151], v[16:31]
	ds_read_b128 v[236:239], v213 offset:34208
	s_waitcnt lgkmcnt(2)
	v_mfma_f32_32x32x16_bf16 v[16:31], v[240:243], v[144:147], v[16:31]
	ds_read_b128 v[240:243], v213 offset:34240
	s_waitcnt lgkmcnt(2)
	v_mfma_f32_32x32x16_bf16 v[16:31], v[244:247], v[140:143], v[16:31]
	ds_read_b128 v[244:247], v213 offset:34272
	s_waitcnt lgkmcnt(2)
	v_mfma_f32_32x32x16_bf16 v[16:31], v[236:239], v[136:139], v[16:31]
	ds_read_b128 v[236:239], v213 offset:50688
	s_waitcnt lgkmcnt(2)
	v_mfma_f32_32x32x16_bf16 v[16:31], v[240:243], v[132:135], v[16:31]
	ds_read_b128 v[240:243], v213 offset:50720
	s_waitcnt lgkmcnt(2)
	v_mfma_f32_32x32x16_bf16 v[16:31], v[244:247], v[128:131], v[16:31]
	ds_read_b128 v[244:247], v213 offset:50752
	s_waitcnt lgkmcnt(2)
	v_mfma_f32_32x32x16_bf16 v[0:15], v[236:239], v[112:115], 0
	ds_read_b128 v[236:239], v213 offset:50784
	s_waitcnt lgkmcnt(2)
	v_mfma_f32_32x32x16_bf16 v[0:15], v[240:243], v[184:187], v[0:15]
	ds_read_b128 v[240:243], v213 offset:50816
	s_waitcnt lgkmcnt(2)
	v_mfma_f32_32x32x16_bf16 v[0:15], v[244:247], v[180:183], v[0:15]
	ds_read_b128 v[244:247], v213 offset:50848
	s_waitcnt lgkmcnt(2)
	v_mfma_f32_32x32x16_bf16 v[0:15], v[236:239], v[176:179], v[0:15]
	ds_read_b128 v[236:239], v213 offset:50880
	s_waitcnt lgkmcnt(2)
	v_mfma_f32_32x32x16_bf16 v[0:15], v[240:243], v[172:175], v[0:15]
	ds_read_b128 v[240:243], v213 offset:50912
	s_waitcnt lgkmcnt(2)
	v_mfma_f32_32x32x16_bf16 v[0:15], v[244:247], v[168:171], v[0:15]
	ds_read_b128 v[244:247], v213 offset:50944
	s_waitcnt lgkmcnt(2)
	v_mfma_f32_32x32x16_bf16 v[0:15], v[236:239], v[164:167], v[0:15]
	ds_read_b128 v[236:239], v213 offset:50976
	s_waitcnt lgkmcnt(2)
	v_mfma_f32_32x32x16_bf16 v[0:15], v[240:243], v[160:163], v[0:15]
	ds_read_b128 v[240:243], v213 offset:51008
	s_waitcnt lgkmcnt(2)
	v_mfma_f32_32x32x16_bf16 v[0:15], v[244:247], v[156:159], v[0:15]
	ds_read_b128 v[244:247], v213 offset:51040
	s_waitcnt lgkmcnt(2)
	v_mfma_f32_32x32x16_bf16 v[0:15], v[236:239], v[152:155], v[0:15]
	ds_read_b128 v[236:239], v213 offset:51072
	s_waitcnt lgkmcnt(2)
	v_mfma_f32_32x32x16_bf16 v[0:15], v[240:243], v[148:151], v[0:15]
	ds_read_b128 v[240:243], v213 offset:51104
	s_waitcnt lgkmcnt(2)
	v_mfma_f32_32x32x16_bf16 v[0:15], v[244:247], v[144:147], v[0:15]
	ds_read_b128 v[244:247], v213 offset:51136
	s_waitcnt lgkmcnt(2)
	v_mfma_f32_32x32x16_bf16 v[0:15], v[236:239], v[140:143], v[0:15]
	ds_read_b128 v[236:239], v213 offset:51168
	s_waitcnt lgkmcnt(2)
	v_mfma_f32_32x32x16_bf16 v[0:15], v[240:243], v[136:139], v[0:15]
	ds_read_b128 v[240:243], v68
	s_waitcnt lgkmcnt(2)
	v_mfma_f32_32x32x16_bf16 v[0:15], v[244:247], v[132:135], v[0:15]
	ds_read_b128 v[244:247], v68 offset:32
	s_waitcnt lgkmcnt(2)
	v_mfma_f32_32x32x16_bf16 v[0:15], v[236:239], v[128:131], v[0:15]
	ds_read_b128 v[236:239], v68 offset:64
	s_waitcnt lgkmcnt(2)
	v_mfma_f32_32x32x16_bf16 v[48:63], v[240:243], v[112:115], 0
	ds_read_b128 v[240:243], v68 offset:96
	s_waitcnt lgkmcnt(2)
	v_mfma_f32_32x32x16_bf16 v[48:63], v[244:247], v[184:187], v[48:63]
	ds_read_b128 v[244:247], v68 offset:128
	s_waitcnt lgkmcnt(2)
	v_mfma_f32_32x32x16_bf16 v[48:63], v[236:239], v[180:183], v[48:63]
	ds_read_b128 v[236:239], v68 offset:160
	s_waitcnt lgkmcnt(2)
	v_mfma_f32_32x32x16_bf16 v[48:63], v[240:243], v[176:179], v[48:63]
	ds_read_b128 v[240:243], v68 offset:192
	s_waitcnt lgkmcnt(2)
	v_mfma_f32_32x32x16_bf16 v[48:63], v[244:247], v[172:175], v[48:63]
	ds_read_b128 v[244:247], v68 offset:224
	s_waitcnt lgkmcnt(2)
	v_mfma_f32_32x32x16_bf16 v[48:63], v[236:239], v[168:171], v[48:63]
	ds_read_b128 v[236:239], v68 offset:256
	s_waitcnt lgkmcnt(2)
	v_mfma_f32_32x32x16_bf16 v[48:63], v[240:243], v[164:167], v[48:63]
	ds_read_b128 v[240:243], v68 offset:288
	s_waitcnt lgkmcnt(2)
	v_mfma_f32_32x32x16_bf16 v[48:63], v[244:247], v[160:163], v[48:63]
	ds_read_b128 v[244:247], v68 offset:320
	s_waitcnt lgkmcnt(2)
	v_mfma_f32_32x32x16_bf16 v[48:63], v[236:239], v[156:159], v[48:63]
	ds_read_b128 v[236:239], v68 offset:352
	s_waitcnt lgkmcnt(2)
	v_mfma_f32_32x32x16_bf16 v[48:63], v[240:243], v[152:155], v[48:63]
	ds_read_b128 v[240:243], v68 offset:384
	s_waitcnt lgkmcnt(2)
	v_mfma_f32_32x32x16_bf16 v[48:63], v[244:247], v[148:151], v[48:63]
	ds_read_b128 v[244:247], v68 offset:416
	s_waitcnt lgkmcnt(2)
	v_mfma_f32_32x32x16_bf16 v[48:63], v[236:239], v[144:147], v[48:63]
	ds_read_b128 v[236:239], v68 offset:448
	s_waitcnt lgkmcnt(2)
	v_mfma_f32_32x32x16_bf16 v[48:63], v[240:243], v[140:143], v[48:63]
	ds_read_b128 v[240:243], v68 offset:480
	s_waitcnt lgkmcnt(2)
	v_mfma_f32_32x32x16_bf16 v[48:63], v[244:247], v[136:139], v[48:63]
	ds_read_b128 v[244:247], v189 offset:16896
	s_waitcnt lgkmcnt(2)
	v_mfma_f32_32x32x16_bf16 v[48:63], v[236:239], v[132:135], v[48:63]
	ds_read_b128 v[236:239], v189 offset:16928
	s_waitcnt lgkmcnt(2)
	v_mfma_f32_32x32x16_bf16 v[48:63], v[240:243], v[128:131], v[48:63]
	ds_read_b128 v[240:243], v189 offset:16960
	s_waitcnt lgkmcnt(2)
	v_mfma_f32_32x32x16_bf16 v[80:95], v[244:247], v[112:115], 0
	ds_read_b128 v[244:247], v189 offset:16992
	s_waitcnt lgkmcnt(2)
	v_mfma_f32_32x32x16_bf16 v[80:95], v[236:239], v[184:187], v[80:95]
	ds_read_b128 v[236:239], v189 offset:17024
	s_waitcnt lgkmcnt(2)
	v_mfma_f32_32x32x16_bf16 v[80:95], v[240:243], v[180:183], v[80:95]
	ds_read_b128 v[240:243], v189 offset:17056
	s_waitcnt lgkmcnt(2)
	v_mfma_f32_32x32x16_bf16 v[80:95], v[244:247], v[176:179], v[80:95]
	ds_read_b128 v[244:247], v189 offset:17088
	s_waitcnt lgkmcnt(2)
; #define LAS __attribute__((address_space(3)))
; __device__ __forceinline__ void xattn_core(unsigned char* ws, LAS unsigned char* lds, int b, int hd, int qb, int tid, const bf16x8 (&qf)[16]) {
;     ...
;     for (int mt = 0; mt < 8; ++mt) {
; #pragma unroll
;         for (int r = 0; r < 16; ++r) sacc[mt][r] = 0.f;
;         const LAS bf16* kp = (mt < 4 ? L0 : L1) + ((mt & 3) * 32 + r32) * XP + 8 * hh;
; #pragma unroll
;         for (int ds = 0; ds < 16; ++ds) { const bf16x8 kf = *(const LAS bf16x8*)(kp + 16 * ds); sacc[mt] = __builtin_amdgcn_mfma_f32_32x32x16_bf16(kf, qf[ds], sacc[mt], 0, 0, 0); } }
;     __syncthreads();
	v_mfma_f32_32x32x16_bf16 v[80:95], v[236:239], v[172:175], v[80:95]
	ds_read_b128 v[236:239], v189 offset:17120
	s_waitcnt lgkmcnt(2)
	v_mfma_f32_32x32x16_bf16 v[80:95], v[240:243], v[168:171], v[80:95]
	ds_read_b128 v[240:243], v189 offset:17152
	s_waitcnt lgkmcnt(2)
	v_mfma_f32_32x32x16_bf16 v[80:95], v[244:247], v[164:167], v[80:95]
	ds_read_b128 v[244:247], v189 offset:17184
	s_waitcnt lgkmcnt(2)
	v_mfma_f32_32x32x16_bf16 v[80:95], v[236:239], v[160:163], v[80:95]
	ds_read_b128 v[236:239], v189 offset:17216
	s_waitcnt lgkmcnt(2)
	v_mfma_f32_32x32x16_bf16 v[80:95], v[240:243], v[156:159], v[80:95]
	ds_read_b128 v[240:243], v189 offset:17248
	s_waitcnt lgkmcnt(2)
	v_mfma_f32_32x32x16_bf16 v[80:95], v[244:247], v[152:155], v[80:95]
	ds_read_b128 v[244:247], v189 offset:17280
	s_waitcnt lgkmcnt(2)
	v_mfma_f32_32x32x16_bf16 v[80:95], v[236:239], v[148:151], v[80:95]
	ds_read_b128 v[236:239], v189 offset:17312
	s_waitcnt lgkmcnt(2)
	v_mfma_f32_32x32x16_bf16 v[80:95], v[240:243], v[144:147], v[80:95]
	ds_read_b128 v[240:243], v189 offset:17344
	s_waitcnt lgkmcnt(2)
	v_mfma_f32_32x32x16_bf16 v[80:95], v[244:247], v[140:143], v[80:95]
	ds_read_b128 v[244:247], v189 offset:17376
	s_waitcnt lgkmcnt(2)
	v_mfma_f32_32x32x16_bf16 v[80:95], v[236:239], v[136:139], v[80:95]
	ds_read_b128 v[236:239], v189 offset:33792
	s_waitcnt lgkmcnt(2)
	v_mfma_f32_32x32x16_bf16 v[80:95], v[240:243], v[132:135], v[80:95]
	ds_read_b128 v[240:243], v189 offset:33824
	s_waitcnt lgkmcnt(2)
	v_mfma_f32_32x32x16_bf16 v[80:95], v[244:247], v[128:131], v[80:95]
	ds_read_b128 v[244:247], v189 offset:33856
	s_waitcnt lgkmcnt(2)
	v_mfma_f32_32x32x16_bf16 v[64:79], v[236:239], v[112:115], 0
	ds_read_b128 v[236:239], v189 offset:33888
	s_waitcnt lgkmcnt(2)
	v_mfma_f32_32x32x16_bf16 v[64:79], v[240:243], v[184:187], v[64:79]
	ds_read_b128 v[240:243], v189 offset:33920
	s_waitcnt lgkmcnt(2)
	v_mfma_f32_32x32x16_bf16 v[64:79], v[244:247], v[180:183], v[64:79]
	ds_read_b128 v[244:247], v189 offset:33952
	s_waitcnt lgkmcnt(2)
	v_mfma_f32_32x32x16_bf16 v[64:79], v[236:239], v[176:179], v[64:79]
	ds_read_b128 v[236:239], v189 offset:33984
	s_waitcnt lgkmcnt(2)
	v_mfma_f32_32x32x16_bf16 v[64:79], v[240:243], v[172:175], v[64:79]
	ds_read_b128 v[240:243], v189 offset:34016
	s_waitcnt lgkmcnt(2)
	v_mfma_f32_32x32x16_bf16 v[64:79], v[244:247], v[168:171], v[64:79]
	ds_read_b128 v[244:247], v189 offset:34048
	s_waitcnt lgkmcnt(2)
	v_mfma_f32_32x32x16_bf16 v[64:79], v[236:239], v[164:167], v[64:79]
	ds_read_b128 v[236:239], v189 offset:34080
	s_waitcnt lgkmcnt(2)
	v_mfma_f32_32x32x16_bf16 v[64:79], v[240:243], v[160:163], v[64:79]
	ds_read_b128 v[240:243], v189 offset:34112
	s_waitcnt lgkmcnt(2)
	v_mfma_f32_32x32x16_bf16 v[64:79], v[244:247], v[156:159], v[64:79]
	ds_read_b128 v[244:247], v189 offset:34144
	s_waitcnt lgkmcnt(2)
	v_mfma_f32_32x32x16_bf16 v[64:79], v[236:239], v[152:155], v[64:79]
	ds_read_b128 v[236:239], v189 offset:34176
	s_waitcnt lgkmcnt(2)
	v_mfma_f32_32x32x16_bf16 v[64:79], v[240:243], v[148:151], v[64:79]
	ds_read_b128 v[240:243], v189 offset:34208
	s_waitcnt lgkmcnt(2)
	v_mfma_f32_32x32x16_bf16 v[64:79], v[244:247], v[144:147], v[64:79]
	ds_read_b128 v[244:247], v189 offset:34240
	s_waitcnt lgkmcnt(2)
	v_mfma_f32_32x32x16_bf16 v[64:79], v[236:239], v[140:143], v[64:79]
	ds_read_b128 v[236:239], v189 offset:34272
	s_waitcnt lgkmcnt(2)
	v_mfma_f32_32x32x16_bf16 v[64:79], v[240:243], v[136:139], v[64:79]
	ds_read_b128 v[240:243], v189 offset:50688
	s_waitcnt lgkmcnt(2)
	v_mfma_f32_32x32x16_bf16 v[64:79], v[244:247], v[132:135], v[64:79]
	ds_read_b128 v[244:247], v189 offset:50720
	s_waitcnt lgkmcnt(2)
	v_mfma_f32_32x32x16_bf16 v[64:79], v[236:239], v[128:131], v[64:79]
	ds_read_b128 v[236:239], v189 offset:50752
	s_waitcnt lgkmcnt(2)
	v_mfma_f32_32x32x16_bf16 v[112:127], v[240:243], v[112:115], 0
	ds_read_b128 v[240:243], v189 offset:50784
	s_waitcnt lgkmcnt(2)
	v_mfma_f32_32x32x16_bf16 v[112:127], v[244:247], v[184:187], v[112:127]
	ds_read_b128 v[244:247], v189 offset:50816
	s_waitcnt lgkmcnt(2)
	v_mfma_f32_32x32x16_bf16 v[112:127], v[236:239], v[180:183], v[112:127]
	ds_read_b128 v[236:239], v189 offset:50848
	s_waitcnt lgkmcnt(2)
	v_mfma_f32_32x32x16_bf16 v[112:127], v[240:243], v[176:179], v[112:127]
	ds_read_b128 v[240:243], v189 offset:50880
	s_waitcnt lgkmcnt(2)
	v_mfma_f32_32x32x16_bf16 v[112:127], v[244:247], v[172:175], v[112:127]
	ds_read_b128 v[244:247], v189 offset:50912
	s_waitcnt lgkmcnt(2)
	v_mfma_f32_32x32x16_bf16 v[112:127], v[236:239], v[168:171], v[112:127]
	ds_read_b128 v[236:239], v189 offset:50944
	s_waitcnt lgkmcnt(2)
	v_mfma_f32_32x32x16_bf16 v[112:127], v[240:243], v[164:167], v[112:127]
	ds_read_b128 v[240:243], v189 offset:50976
	s_waitcnt lgkmcnt(2)
	v_mfma_f32_32x32x16_bf16 v[112:127], v[244:247], v[160:163], v[112:127]
	ds_read_b128 v[244:247], v189 offset:51008
	s_waitcnt lgkmcnt(2)
	v_mfma_f32_32x32x16_bf16 v[112:127], v[236:239], v[156:159], v[112:127]
	v_lshl_add_u64 v[160:161], s[16:17], 0, v[190:191]
	ds_read_b128 v[236:239], v189 offset:51040
	s_waitcnt lgkmcnt(2)
	v_mfma_f32_32x32x16_bf16 v[112:127], v[240:243], v[152:155], v[112:127]
	v_lshl_add_u64 v[156:157], v[160:161], 0, s[14:15]
	s_mov_b64 s[14:15], 0x5840000
	ds_read_b128 v[240:243], v189 offset:51072
	s_waitcnt lgkmcnt(2)
	v_mfma_f32_32x32x16_bf16 v[112:127], v[244:247], v[148:151], v[112:127]
	v_lshl_add_u64 v[152:153], v[156:157], 0, v[204:205]
	ds_read_b128 v[244:247], v189 offset:51104
	s_waitcnt lgkmcnt(2)
	v_mfma_f32_32x32x16_bf16 v[112:127], v[236:239], v[144:147], v[112:127]
	v_lshl_add_u64 v[148:149], v[156:157], 0, v[202:203]
	ds_read_b128 v[236:239], v189 offset:51136
	s_waitcnt lgkmcnt(2)
	v_mfma_f32_32x32x16_bf16 v[112:127], v[240:243], v[140:143], v[112:127]
	v_lshl_add_u64 v[144:145], v[156:157], 0, v[200:201]
	ds_read_b128 v[240:243], v189 offset:51168
	s_waitcnt lgkmcnt(2)
	v_mfma_f32_32x32x16_bf16 v[112:127], v[244:247], v[136:139], v[112:127]
	v_lshl_add_u64 v[140:141], v[156:157], 0, v[198:199]
	s_waitcnt lgkmcnt(1)
	v_mfma_f32_32x32x16_bf16 v[112:127], v[236:239], v[132:135], v[112:127]
	s_waitcnt lgkmcnt(0)
	s_barrier
; #define LAS __attribute__((address_space(3)))
; __device__ __forceinline__ void stage_half(const bf16* g, LAS bf16* dst, int tid) {
;     v4u t[8];
; #pragma unroll
;     for (int i = 0; i < 8; ++i) { const int ch = tid + i * NT, r = ch >> 5, cc = ch & 31; t[i] = *(const v4u*)(g + (size_t)r * 1024 + cc * 8); }
; #pragma unroll
;     for (int i = 0; i < 8; ++i) { const int ch = tid + i * NT, r = ch >> 5, cc = ch & 31; *(LAS v4u*)(dst + r * XP + cc * 8) = t[i]; }
; }
; __device__ __forceinline__ void xattn_core(unsigned char* ws, LAS unsigned char* lds, int b, int hd, int qb, int tid, const bf16x8 (&qf)[16]) {
;     ...
;     __syncthreads();
;     stage_half(Vg, L0, tid); stage_half(Vg + (size_t)128 * 1024, L1, tid);
;     float mx = -3.0e38f;
; #pragma unroll
;     for (int mt = 0; mt < 8; ++mt)
; #pragma unroll
;         for (int r = 0; r < 16; ++r) mx = fmaxf(mx, sacc[mt][r]);
;     mx = fmaxf(mx, __shfl_xor(mx, 32));
	v_lshl_add_u64 v[136:137], v[156:157], 0, v[196:197]
	global_load_dwordx4 v[136:139], v[136:137], off
	v_mov_b32_e32 v189, v191
	s_waitcnt lgkmcnt(0)
	v_mfma_f32_32x32x16_bf16 v[112:127], v[240:243], v[128:131], v[112:127]
	v_lshl_add_u64 v[128:129], v[156:157], 0, v[192:193]
	global_load_dwordx4 v[128:131], v[128:129], off
	v_lshl_add_u64 v[132:133], v[156:157], 0, v[194:195]
	global_load_dwordx4 v[132:135], v[132:133], off
	v_lshl_add_u64 v[156:157], v[156:157], 0, v[206:207]
	global_load_dwordx4 v[140:143], v[140:141], off
	s_nop 0
	global_load_dwordx4 v[144:147], v[144:145], off
	s_nop 0
	global_load_dwordx4 v[148:151], v[148:149], off
	s_nop 0
	global_load_dwordx4 v[152:155], v[152:153], off
	s_nop 0
	global_load_dwordx4 v[156:159], v[156:157], off
	s_waitcnt vmcnt(6)
	ds_write_b128 v223, v[128:131]
	s_waitcnt vmcnt(5)
	ds_write_b128 v222, v[132:135]
	ds_write_b128 v221, v[136:139]
	s_waitcnt vmcnt(4)
	ds_write_b128 v220, v[140:143]
	s_waitcnt vmcnt(3)
	ds_write_b128 v219, v[144:147]
	s_waitcnt vmcnt(2)
	ds_write_b128 v218, v[148:151]
	s_waitcnt vmcnt(1)
	ds_write_b128 v217, v[152:155]
	s_waitcnt vmcnt(0)
	ds_write_b128 v216, v[156:159]
	v_lshl_add_u64 v[156:157], v[160:161], 0, s[14:15]
	v_lshl_add_u64 v[128:129], v[156:157], 0, v[192:193]
	global_load_dwordx4 v[128:131], v[128:129], off
	v_lshl_add_u64 v[132:133], v[156:157], 0, v[194:195]
	global_load_dwordx4 v[132:135], v[132:133], off
	v_lshl_add_u64 v[136:137], v[156:157], 0, v[196:197]
	global_load_dwordx4 v[136:139], v[136:137], off
	v_lshl_add_u64 v[140:141], v[156:157], 0, v[198:199]
	global_load_dwordx4 v[140:143], v[140:141], off
	v_lshl_add_u64 v[144:145], v[156:157], 0, v[200:201]
	global_load_dwordx4 v[144:147], v[144:145], off
	v_lshl_add_u64 v[148:149], v[156:157], 0, v[202:203]
	global_load_dwordx4 v[148:151], v[148:149], off
	v_lshl_add_u64 v[152:153], v[156:157], 0, v[204:205]
	global_load_dwordx4 v[152:155], v[152:153], off
	v_lshl_add_u64 v[156:157], v[156:157], 0, v[206:207]
	global_load_dwordx4 v[156:159], v[156:157], off
	s_waitcnt vmcnt(7)
	ds_write_b128 v230, v[128:131]
	s_waitcnt vmcnt(6)
	ds_write_b128 v224, v[132:135]
	s_waitcnt vmcnt(5)
	ds_write_b128 v225, v[136:139]
	s_waitcnt vmcnt(4)
	ds_write_b128 v226, v[140:143]
	s_waitcnt vmcnt(3)
	ds_write_b128 v227, v[144:147]
	s_waitcnt vmcnt(2)
	ds_write_b128 v228, v[148:151]
	s_waitcnt vmcnt(1)
	ds_write_b128 v229, v[152:155]
	s_waitcnt vmcnt(0)
	ds_write_b128 v215, v[156:159]
	v_max3_f32 v128, v96, s7, v97
	v_max3_f32 v128, v128, v98, v99
	v_max3_f32 v128, v128, v100, v101
	v_max3_f32 v128, v128, v102, v103
	v_max3_f32 v128, v128, v104, v105
	v_max3_f32 v128, v128, v106, v107
	v_max3_f32 v128, v128, v108, v109
	v_max3_f32 v128, v128, v110, v111
	v_max3_f32 v128, v128, v32, v33
	v_max3_f32 v128, v128, v34, v35
	v_max3_f32 v128, v128, v36, v37
	v_max3_f32 v128, v128, v38, v39
	v_max3_f32 v128, v128, v40, v41
	v_max3_f32 v128, v128, v42, v43
	v_max3_f32 v128, v128, v44, v45
	v_max3_f32 v128, v128, v46, v47
	v_max3_f32 v128, v128, v16, v17
	v_max3_f32 v128, v128, v18, v19
	v_max3_f32 v128, v128, v20, v21
	v_max3_f32 v128, v128, v22, v23
	v_max3_f32 v128, v128, v24, v25
	v_max3_f32 v128, v128, v26, v27
	v_max3_f32 v128, v128, v28, v29
	v_max3_f32 v128, v128, v30, v31
	v_max3_f32 v128, v128, v0, v1
	v_max3_f32 v128, v128, v2, v3
	v_max3_f32 v128, v128, v4, v5
	v_max3_f32 v128, v128, v6, v7
	v_max3_f32 v128, v128, v8, v9
	v_max3_f32 v128, v128, v10, v11
	v_max3_f32 v128, v128, v12, v13
	v_max3_f32 v128, v128, v14, v15
	v_max3_f32 v128, v128, v48, v49
	v_max3_f32 v128, v128, v50, v51
	v_max3_f32 v128, v128, v52, v53
	v_max3_f32 v128, v128, v54, v55
	v_max3_f32 v128, v128, v56, v57
	v_max3_f32 v128, v128, v58, v59
	v_max3_f32 v128, v128, v60, v61
	v_max3_f32 v128, v128, v62, v63
	v_max3_f32 v128, v128, v80, v81
	v_max3_f32 v128, v128, v82, v83
	v_max3_f32 v128, v128, v84, v85
	v_max3_f32 v128, v128, v86, v87
	v_max3_f32 v128, v128, v88, v89
	v_max3_f32 v128, v128, v90, v91
	v_max3_f32 v128, v128, v92, v93
	v_max3_f32 v128, v128, v94, v95
	v_max3_f32 v128, v128, v64, v65
	v_max3_f32 v128, v128, v66, v67
	v_max3_f32 v128, v128, v68, v69
	v_max3_f32 v128, v128, v70, v71
	v_max3_f32 v128, v128, v72, v73
	v_max3_f32 v128, v128, v74, v75
	v_max3_f32 v128, v128, v76, v77
	v_max3_f32 v128, v128, v78, v79
	v_max3_f32 v128, v128, v112, v113
	v_max3_f32 v128, v128, v114, v115
	v_max3_f32 v128, v128, v116, v117
	v_max3_f32 v128, v128, v118, v119
	v_max3_f32 v128, v128, v120, v121
	v_max3_f32 v128, v128, v122, v123
	v_max3_f32 v128, v128, v124, v125
	v_max3_f32 v129, v128, v126, v127
	v_mbcnt_lo_u32_b32 v128, -1, 0
	v_mbcnt_hi_u32_b32 v128, -1, v128
	v_and_b32_e32 v131, 64, v128
	v_xor_b32_e32 v130, 32, v128
	v_add_u32_e32 v131, 64, v131
	v_cmp_lt_i32_e32 vcc, v130, v131
	s_waitcnt lgkmcnt(0)
	s_barrier
; __device__ __forceinline__ unsigned pk2(float lo, float hi) { return pg8::cvt_pk_bf16(lo, hi); }
; __device__ __forceinline__ void xattn_core(unsigned char* ws, LAS unsigned char* lds, int b, int hd, int qb, int tid, const bf16x8 (&qf)[16]) {
;     ...
;     mx = fmaxf(mx, __shfl_xor(mx, 32));
;     float sum = 0.f; bf16x8 pf[8][2];
; #pragma unroll
;     for (int mt = 0; mt < 8; ++mt) {
;         float e[16];
; #pragma unroll
;         for (int r = 0; r < 16; ++r) { e[r] = __expf(sacc[mt][r] - mx); sum += e[r]; }
; #pragma unroll
;         for (int s = 0; s < 2; ++s) { v4u w; w.x = pk2(e[8 * s], e[8 * s + 1]); w.y = pk2(e[8 * s + 2], e[8 * s + 3]); w.z = pk2(e[8 * s + 4], e[8 * s + 5]); w.w = pk2(e[8 * s + 6], e[8 * s + 7]); pf[mt][s] = __builtin_bit_cast(bf16x8, w); }
	v_cndmask_b32_e32 v128, v128, v130, vcc
	v_lshlrev_b32_e32 v128, 2, v128
	ds_bpermute_b32 v130, v128, v129
	s_waitcnt lgkmcnt(0)
	v_max_f32_e32 v130, v130, v130
	v_max_f32_e32 v129, v129, v130
	v_sub_f32_e32 v96, v96, v129
	v_mul_f32_e32 v96, 0x3fb8aa3b, v96
	v_exp_f32_e32 v130, v96
	v_sub_f32_e32 v96, v97, v129
	v_mul_f32_e32 v96, 0x3fb8aa3b, v96
	v_exp_f32_e32 v131, v96
	v_sub_f32_e32 v96, v98, v129
	v_mul_f32_e32 v96, 0x3fb8aa3b, v96
	v_exp_f32_e32 v132, v96
	v_sub_f32_e32 v96, v99, v129
	v_mul_f32_e32 v96, 0x3fb8aa3b, v96
	v_exp_f32_e32 v133, v96
	v_sub_f32_e32 v96, v100, v129
	v_mul_f32_e32 v96, 0x3fb8aa3b, v96
	v_exp_f32_e32 v134, v96
	v_sub_f32_e32 v96, v101, v129
	v_mul_f32_e32 v96, 0x3fb8aa3b, v96
	v_exp_f32_e32 v135, v96
	v_sub_f32_e32 v96, v102, v129
	v_mul_f32_e32 v96, 0x3fb8aa3b, v96
	v_exp_f32_e32 v136, v96
	v_sub_f32_e32 v96, v103, v129
	v_mul_f32_e32 v96, 0x3fb8aa3b, v96
	v_exp_f32_e32 v137, v96
	v_sub_f32_e32 v96, v104, v129
	v_mul_f32_e32 v96, 0x3fb8aa3b, v96
	v_exp_f32_e32 v104, v96
	v_sub_f32_e32 v96, v105, v129
	v_mul_f32_e32 v96, 0x3fb8aa3b, v96
	v_exp_f32_e32 v105, v96
	v_sub_f32_e32 v96, v106, v129
	v_mul_f32_e32 v96, 0x3fb8aa3b, v96
	v_exp_f32_e32 v106, v96
	v_sub_f32_e32 v96, v107, v129
	v_mul_f32_e32 v96, 0x3fb8aa3b, v96
	v_exp_f32_e32 v107, v96
	v_sub_f32_e32 v96, v108, v129
	v_mul_f32_e32 v96, 0x3fb8aa3b, v96
	v_exp_f32_e32 v108, v96
	v_sub_f32_e32 v96, v109, v129
	v_mul_f32_e32 v96, 0x3fb8aa3b, v96
	v_exp_f32_e32 v109, v96
	v_sub_f32_e32 v96, v110, v129
	v_mul_f32_e32 v96, 0x3fb8aa3b, v96
	v_exp_f32_e32 v110, v96
	v_sub_f32_e32 v96, v111, v129
	v_mul_f32_e32 v96, 0x3fb8aa3b, v96
	v_exp_f32_e32 v111, v96
	v_cvt_pk_bf16_f32 v96, v130, v131
	v_add_f32_e32 v130, 0, v130
	v_add_f32_e32 v130, v131, v130
	v_add_f32_e32 v130, v132, v130
	v_add_f32_e32 v130, v133, v130
	v_add_f32_e32 v130, v134, v130
	v_add_f32_e32 v130, v135, v130
	v_add_f32_e32 v130, v136, v130
	v_add_f32_e32 v130, v137, v130
	v_sub_f32_e32 v32, v32, v129
	v_cvt_pk_bf16_f32 v100, v104, v105
	v_add_f32_e32 v104, v104, v130
	v_mul_f32_e32 v32, 0x3fb8aa3b, v32
	v_add_f32_e32 v104, v105, v104
	v_exp_f32_e32 v105, v32
	v_sub_f32_e32 v32, v33, v129
	v_mul_f32_e32 v32, 0x3fb8aa3b, v32
	v_cvt_pk_bf16_f32 v101, v106, v107
	v_add_f32_e32 v104, v106, v104
	v_exp_f32_e32 v106, v32
	v_sub_f32_e32 v32, v34, v129
	v_mul_f32_e32 v32, 0x3fb8aa3b, v32
	v_add_f32_e32 v104, v107, v104
	v_exp_f32_e32 v107, v32
	v_sub_f32_e32 v32, v35, v129
	v_mul_f32_e32 v32, 0x3fb8aa3b, v32
	v_cvt_pk_bf16_f32 v102, v108, v109
	v_add_f32_e32 v104, v108, v104
	v_exp_f32_e32 v108, v32
	v_sub_f32_e32 v32, v36, v129
	v_mul_f32_e32 v32, 0x3fb8aa3b, v32
	v_add_f32_e32 v104, v109, v104
	v_exp_f32_e32 v109, v32
	v_sub_f32_e32 v32, v37, v129
	v_mul_f32_e32 v32, 0x3fb8aa3b, v32
	v_cvt_pk_bf16_f32 v103, v110, v111
	v_add_f32_e32 v104, v110, v104
	v_exp_f32_e32 v110, v32
	v_sub_f32_e32 v32, v38, v129
	v_mul_f32_e32 v32, 0x3fb8aa3b, v32
	v_add_f32_e32 v104, v111, v104
	v_exp_f32_e32 v111, v32
	v_sub_f32_e32 v32, v39, v129
	v_mul_f32_e32 v32, 0x3fb8aa3b, v32
	v_exp_f32_e32 v130, v32
	v_sub_f32_e32 v32, v40, v129
	v_mul_f32_e32 v32, 0x3fb8aa3b, v32
	v_add_f32_e32 v104, v105, v104
	v_exp_f32_e32 v40, v32
	v_sub_f32_e32 v32, v41, v129
	v_add_f32_e32 v104, v106, v104
	v_mul_f32_e32 v32, 0x3fb8aa3b, v32
	v_add_f32_e32 v104, v107, v104
	v_exp_f32_e32 v41, v32
	v_sub_f32_e32 v32, v42, v129
	v_add_f32_e32 v104, v108, v104
	v_mul_f32_e32 v32, 0x3fb8aa3b, v32
	v_add_f32_e32 v104, v109, v104
	v_exp_f32_e32 v42, v32
	v_sub_f32_e32 v32, v43, v129
	v_add_f32_e32 v104, v110, v104
	v_mul_f32_e32 v32, 0x3fb8aa3b, v32
	v_add_f32_e32 v104, v111, v104
	v_exp_f32_e32 v43, v32
	v_sub_f32_e32 v32, v44, v129
	v_add_f32_e32 v104, v130, v104
	v_sub_f32_e32 v16, v16, v129
	v_mul_f32_e32 v32, 0x3fb8aa3b, v32
	v_cvt_pk_bf16_f32 v36, v40, v41
	v_add_f32_e32 v40, v40, v104
	v_mul_f32_e32 v16, 0x3fb8aa3b, v16
	v_exp_f32_e32 v44, v32
	v_sub_f32_e32 v32, v45, v129
	v_add_f32_e32 v40, v41, v40
	v_exp_f32_e32 v41, v16
	v_sub_f32_e32 v16, v17, v129
	v_mul_f32_e32 v32, 0x3fb8aa3b, v32
	v_mul_f32_e32 v16, 0x3fb8aa3b, v16
	v_exp_f32_e32 v45, v32
	v_sub_f32_e32 v32, v46, v129
	v_cvt_pk_bf16_f32 v37, v42, v43
	v_add_f32_e32 v40, v42, v40
	v_exp_f32_e32 v42, v16
	v_sub_f32_e32 v16, v18, v129
	v_mul_f32_e32 v32, 0x3fb8aa3b, v32
	v_mul_f32_e32 v16, 0x3fb8aa3b, v16
	v_exp_f32_e32 v46, v32
	v_sub_f32_e32 v32, v47, v129
	v_add_f32_e32 v40, v43, v40
	v_exp_f32_e32 v43, v16
	v_sub_f32_e32 v16, v19, v129
	v_mul_f32_e32 v32, 0x3fb8aa3b, v32
	v_mul_f32_e32 v16, 0x3fb8aa3b, v16
	v_exp_f32_e32 v47, v32
	v_cvt_pk_bf16_f32 v38, v44, v45
	v_add_f32_e32 v40, v44, v40
	v_exp_f32_e32 v44, v16
	v_sub_f32_e32 v16, v20, v129
	v_mul_f32_e32 v16, 0x3fb8aa3b, v16
	v_add_f32_e32 v40, v45, v40
	v_exp_f32_e32 v45, v16
	v_sub_f32_e32 v16, v21, v129
	v_mul_f32_e32 v16, 0x3fb8aa3b, v16
	v_cvt_pk_bf16_f32 v39, v46, v47
	v_add_f32_e32 v40, v46, v40
	v_exp_f32_e32 v46, v16
	v_sub_f32_e32 v16, v22, v129
	v_mul_f32_e32 v16, 0x3fb8aa3b, v16
	v_add_f32_e32 v40, v47, v40
	v_exp_f32_e32 v47, v16
	v_sub_f32_e32 v16, v23, v129
	v_mul_f32_e32 v16, 0x3fb8aa3b, v16
	v_exp_f32_e32 v104, v16
	v_sub_f32_e32 v16, v24, v129
	v_mul_f32_e32 v16, 0x3fb8aa3b, v16
	v_exp_f32_e32 v24, v16
	v_sub_f32_e32 v16, v25, v129
	v_mul_f32_e32 v16, 0x3fb8aa3b, v16
	v_exp_f32_e32 v25, v16
	v_sub_f32_e32 v16, v26, v129
	v_mul_f32_e32 v16, 0x3fb8aa3b, v16
	v_add_f32_e32 v40, v41, v40
	v_exp_f32_e32 v26, v16
	v_sub_f32_e32 v16, v27, v129
	v_add_f32_e32 v40, v42, v40
	v_mul_f32_e32 v16, 0x3fb8aa3b, v16
	v_add_f32_e32 v40, v43, v40
	v_exp_f32_e32 v27, v16
	v_sub_f32_e32 v16, v28, v129
	v_add_f32_e32 v40, v44, v40
; __device__ __forceinline__ unsigned pk2(float lo, float hi) { return pg8::cvt_pk_bf16(lo, hi); }
; __device__ __forceinline__ void xattn_core(unsigned char* ws, LAS unsigned char* lds, int b, int hd, int qb, int tid, const bf16x8 (&qf)[16]) {
;     ...
;     for (int mt = 0; mt < 8; ++mt) {
;         float e[16];
; #pragma unroll
;         for (int r = 0; r < 16; ++r) { e[r] = __expf(sacc[mt][r] - mx); sum += e[r]; }
; #pragma unroll
;         for (int s = 0; s < 2; ++s) { v4u w; w.x = pk2(e[8 * s], e[8 * s + 1]); w.y = pk2(e[8 * s + 2], e[8 * s + 3]); w.z = pk2(e[8 * s + 4], e[8 * s + 5]); w.w = pk2(e[8 * s + 6], e[8 * s + 7]); pf[mt][s] = __builtin_bit_cast(bf16x8, w); }
	v_mul_f32_e32 v16, 0x3fb8aa3b, v16
	v_add_f32_e32 v40, v45, v40
	v_exp_f32_e32 v28, v16
	v_sub_f32_e32 v16, v29, v129
	v_add_f32_e32 v40, v46, v40
	v_mul_f32_e32 v16, 0x3fb8aa3b, v16
	v_add_f32_e32 v40, v47, v40
	v_exp_f32_e32 v29, v16
	v_sub_f32_e32 v16, v30, v129
	v_add_f32_e32 v40, v104, v40
	v_mul_f32_e32 v16, 0x3fb8aa3b, v16
	v_cvt_pk_bf16_f32 v20, v24, v25
	v_add_f32_e32 v24, v24, v40
	v_exp_f32_e32 v30, v16
	v_sub_f32_e32 v16, v31, v129
	v_add_f32_e32 v24, v25, v24
	v_mul_f32_e32 v16, 0x3fb8aa3b, v16
	v_add_f32_e32 v24, v26, v24
	v_sub_f32_e32 v0, v0, v129
	v_sub_f32_e32 v1, v1, v129
	v_exp_f32_e32 v31, v16
	v_add_f32_e32 v24, v27, v24
	v_mul_f32_e32 v0, 0x3fb8aa3b, v0
	v_mul_f32_e32 v1, 0x3fb8aa3b, v1
	v_add_f32_e32 v24, v28, v24
	v_exp_f32_e32 v0, v0
	v_exp_f32_e32 v1, v1
	v_sub_f32_e32 v2, v2, v129
	v_add_f32_e32 v24, v29, v24
	v_mul_f32_e32 v2, 0x3fb8aa3b, v2
	v_sub_f32_e32 v3, v3, v129
	v_add_f32_e32 v24, v30, v24
	v_exp_f32_e32 v2, v2
	v_mul_f32_e32 v3, 0x3fb8aa3b, v3
	v_sub_f32_e32 v4, v4, v129
	v_add_f32_e32 v40, v31, v24
	v_exp_f32_e32 v3, v3
	v_mul_f32_e32 v4, 0x3fb8aa3b, v4
	v_sub_f32_e32 v5, v5, v129
	v_exp_f32_e32 v4, v4
	v_mul_f32_e32 v5, 0x3fb8aa3b, v5
	v_sub_f32_e32 v6, v6, v129
	v_cvt_pk_bf16_f32 v24, v0, v1
	v_add_f32_e32 v0, v0, v40
	v_exp_f32_e32 v5, v5
	v_mul_f32_e32 v6, 0x3fb8aa3b, v6
	v_sub_f32_e32 v7, v7, v129
	v_add_f32_e32 v0, v1, v0
	v_exp_f32_e32 v6, v6
	v_mul_f32_e32 v7, 0x3fb8aa3b, v7
	v_sub_f32_e32 v8, v8, v129
	v_add_f32_e32 v0, v2, v0
	v_exp_f32_e32 v7, v7
	v_mul_f32_e32 v8, 0x3fb8aa3b, v8
	v_sub_f32_e32 v9, v9, v129
	v_add_f32_e32 v0, v3, v0
	v_exp_f32_e32 v8, v8
	v_mul_f32_e32 v9, 0x3fb8aa3b, v9
	v_sub_f32_e32 v10, v10, v129
	v_add_f32_e32 v0, v4, v0
	v_exp_f32_e32 v9, v9
	v_mul_f32_e32 v10, 0x3fb8aa3b, v10
	v_sub_f32_e32 v11, v11, v129
	v_add_f32_e32 v0, v5, v0
	v_exp_f32_e32 v10, v10
	v_mul_f32_e32 v11, 0x3fb8aa3b, v11
	v_sub_f32_e32 v12, v12, v129
	v_add_f32_e32 v0, v6, v0
	v_exp_f32_e32 v11, v11
	v_mul_f32_e32 v12, 0x3fb8aa3b, v12
	v_sub_f32_e32 v13, v13, v129
	v_add_f32_e32 v0, v7, v0
	v_exp_f32_e32 v12, v12
	v_mul_f32_e32 v13, 0x3fb8aa3b, v13
	v_sub_f32_e32 v14, v14, v129
	v_add_f32_e32 v0, v8, v0
	v_exp_f32_e32 v13, v13
	v_mul_f32_e32 v14, 0x3fb8aa3b, v14
	v_sub_f32_e32 v15, v15, v129
	v_add_f32_e32 v0, v9, v0
	v_exp_f32_e32 v14, v14
	v_mul_f32_e32 v15, 0x3fb8aa3b, v15
	v_add_f32_e32 v0, v10, v0
	v_sub_f32_e32 v1, v48, v129
	v_exp_f32_e32 v15, v15
	v_cvt_pk_bf16_f32 v25, v2, v3
	v_add_f32_e32 v0, v11, v0
	v_mul_f32_e32 v1, 0x3fb8aa3b, v1
	v_sub_f32_e32 v2, v49, v129
	v_add_f32_e32 v0, v12, v0
	v_exp_f32_e32 v1, v1
	v_mul_f32_e32 v2, 0x3fb8aa3b, v2
	v_sub_f32_e32 v3, v50, v129
	v_cvt_pk_bf16_f32 v21, v26, v27
	v_cvt_pk_bf16_f32 v26, v4, v5
	v_add_f32_e32 v0, v13, v0
	v_exp_f32_e32 v2, v2
	v_mul_f32_e32 v3, 0x3fb8aa3b, v3
	v_sub_f32_e32 v4, v51, v129
	v_add_f32_e32 v0, v14, v0
	v_exp_f32_e32 v3, v3
	v_mul_f32_e32 v4, 0x3fb8aa3b, v4
	v_sub_f32_e32 v5, v52, v129
	v_cvt_pk_bf16_f32 v27, v6, v7
	v_add_f32_e32 v0, v15, v0
	v_exp_f32_e32 v4, v4
	v_mul_f32_e32 v5, 0x3fb8aa3b, v5
	v_sub_f32_e32 v6, v53, v129
	v_exp_f32_e32 v5, v5
	v_mul_f32_e32 v6, 0x3fb8aa3b, v6
	v_sub_f32_e32 v7, v54, v129
	v_add_f32_e32 v0, v1, v0
	v_cvt_pk_bf16_f32 v22, v28, v29
	v_cvt_pk_bf16_f32 v28, v8, v9
	v_exp_f32_e32 v6, v6
	v_mul_f32_e32 v7, 0x3fb8aa3b, v7
	v_sub_f32_e32 v8, v55, v129
	v_add_f32_e32 v0, v2, v0
	v_exp_f32_e32 v7, v7
	v_mul_f32_e32 v8, 0x3fb8aa3b, v8
	v_sub_f32_e32 v9, v56, v129
	v_add_f32_e32 v0, v3, v0
	v_cvt_pk_bf16_f32 v29, v10, v11
	v_exp_f32_e32 v8, v8
	v_mul_f32_e32 v9, 0x3fb8aa3b, v9
	v_sub_f32_e32 v10, v57, v129
	v_add_f32_e32 v0, v4, v0
	v_exp_f32_e32 v9, v9
	v_mul_f32_e32 v10, 0x3fb8aa3b, v10
	v_sub_f32_e32 v11, v58, v129
	v_add_f32_e32 v0, v5, v0
	v_cvt_pk_bf16_f32 v23, v30, v31
	v_cvt_pk_bf16_f32 v30, v12, v13
	v_exp_f32_e32 v10, v10
	v_mul_f32_e32 v11, 0x3fb8aa3b, v11
	v_sub_f32_e32 v12, v59, v129
	v_add_f32_e32 v0, v6, v0
	v_exp_f32_e32 v11, v11
	v_mul_f32_e32 v12, 0x3fb8aa3b, v12
	v_sub_f32_e32 v13, v60, v129
	v_add_f32_e32 v0, v7, v0
	v_cvt_pk_bf16_f32 v31, v14, v15
	v_exp_f32_e32 v12, v12
	v_mul_f32_e32 v13, 0x3fb8aa3b, v13
	v_sub_f32_e32 v14, v61, v129
	v_add_f32_e32 v0, v8, v0
	v_exp_f32_e32 v13, v13
	v_mul_f32_e32 v14, 0x3fb8aa3b, v14
	v_sub_f32_e32 v15, v62, v129
	v_sub_f32_e32 v40, v63, v129
	v_add_f32_e32 v0, v9, v0
	v_exp_f32_e32 v14, v14
	v_mul_f32_e32 v15, 0x3fb8aa3b, v15
	v_mul_f32_e32 v40, 0x3fb8aa3b, v40
	v_add_f32_e32 v0, v10, v0
	v_exp_f32_e32 v15, v15
	v_exp_f32_e32 v48, v40
	v_cvt_pk_bf16_f32 v40, v1, v2
	v_add_f32_e32 v0, v11, v0
	v_sub_f32_e32 v1, v80, v129
	v_add_f32_e32 v0, v12, v0
	v_mul_f32_e32 v1, 0x3fb8aa3b, v1
	v_sub_f32_e32 v2, v81, v129
	v_cvt_pk_bf16_f32 v16, v41, v42
	v_cvt_pk_bf16_f32 v41, v3, v4
	v_add_f32_e32 v0, v13, v0
	v_exp_f32_e32 v1, v1
	v_mul_f32_e32 v2, 0x3fb8aa3b, v2
	v_sub_f32_e32 v3, v82, v129
	v_add_f32_e32 v0, v14, v0
	v_exp_f32_e32 v2, v2
	v_mul_f32_e32 v3, 0x3fb8aa3b, v3
	v_sub_f32_e32 v4, v83, v129
	v_cvt_pk_bf16_f32 v42, v5, v6
	v_add_f32_e32 v0, v15, v0
	v_exp_f32_e32 v3, v3
	v_mul_f32_e32 v4, 0x3fb8aa3b, v4
	v_sub_f32_e32 v5, v84, v129
	v_add_f32_e32 v0, v48, v0
	v_exp_f32_e32 v4, v4
	v_mul_f32_e32 v5, 0x3fb8aa3b, v5
	v_sub_f32_e32 v6, v85, v129
	v_cvt_pk_bf16_f32 v17, v43, v44
	v_cvt_pk_bf16_f32 v43, v7, v8
	v_exp_f32_e32 v5, v5
	v_mul_f32_e32 v6, 0x3fb8aa3b, v6
	v_sub_f32_e32 v7, v86, v129
	v_add_f32_e32 v0, v1, v0
	v_exp_f32_e32 v6, v6
	v_mul_f32_e32 v7, 0x3fb8aa3b, v7
	v_sub_f32_e32 v8, v87, v129
	v_add_f32_e32 v0, v2, v0
	v_cvt_pk_bf16_f32 v44, v9, v10
	v_exp_f32_e32 v7, v7
	v_mul_f32_e32 v8, 0x3fb8aa3b, v8
	v_sub_f32_e32 v9, v88, v129
; __device__ __forceinline__ unsigned pk2(float lo, float hi) { return pg8::cvt_pk_bf16(lo, hi); }
; __device__ __forceinline__ void xattn_core(unsigned char* ws, LAS unsigned char* lds, int b, int hd, int qb, int tid, const bf16x8 (&qf)[16]) {
;     ...
;     for (int mt = 0; mt < 8; ++mt) {
;         float e[16];
; #pragma unroll
;         for (int r = 0; r < 16; ++r) { e[r] = __expf(sacc[mt][r] - mx); sum += e[r]; }
; #pragma unroll
;         for (int s = 0; s < 2; ++s) { v4u w; w.x = pk2(e[8 * s], e[8 * s + 1]); w.y = pk2(e[8 * s + 2], e[8 * s + 3]); w.z = pk2(e[8 * s + 4], e[8 * s + 5]); w.w = pk2(e[8 * s + 6], e[8 * s + 7]); pf[mt][s] = __builtin_bit_cast(bf16x8, w); }
;     }
;     sum += __shfl_xor(sum, 32);
;     const float inv = 1.f / sum;
;     __syncthreads();
;     bf16* op = (bf16*)(ws + WS_O) + (size_t)(q0 + r32) * 1024 + hd * 256 + 4 * hh;
	v_add_f32_e32 v0, v3, v0
	v_exp_f32_e32 v8, v8
	v_mul_f32_e32 v9, 0x3fb8aa3b, v9
	v_sub_f32_e32 v10, v89, v129
	v_add_f32_e32 v0, v4, v0
	v_cvt_pk_bf16_f32 v18, v45, v46
	v_cvt_pk_bf16_f32 v45, v11, v12
	v_exp_f32_e32 v9, v9
	v_mul_f32_e32 v10, 0x3fb8aa3b, v10
	v_sub_f32_e32 v11, v90, v129
	v_add_f32_e32 v0, v5, v0
	v_exp_f32_e32 v10, v10
	v_mul_f32_e32 v11, 0x3fb8aa3b, v11
	v_sub_f32_e32 v12, v91, v129
	v_add_f32_e32 v0, v6, v0
	v_cvt_pk_bf16_f32 v46, v13, v14
	v_exp_f32_e32 v11, v11
	v_mul_f32_e32 v12, 0x3fb8aa3b, v12
	v_sub_f32_e32 v13, v92, v129
	v_add_f32_e32 v0, v7, v0
	v_exp_f32_e32 v12, v12
	v_mul_f32_e32 v13, 0x3fb8aa3b, v13
	v_sub_f32_e32 v14, v93, v129
	v_add_f32_e32 v0, v8, v0
	v_cvt_pk_bf16_f32 v19, v47, v104
	v_cvt_pk_bf16_f32 v47, v15, v48
	v_exp_f32_e32 v13, v13
	v_mul_f32_e32 v14, 0x3fb8aa3b, v14
	v_sub_f32_e32 v15, v94, v129
	v_sub_f32_e32 v48, v95, v129
	v_add_f32_e32 v0, v9, v0
	v_exp_f32_e32 v14, v14
	v_mul_f32_e32 v15, 0x3fb8aa3b, v15
	v_mul_f32_e32 v48, 0x3fb8aa3b, v48
	v_add_f32_e32 v0, v10, v0
	v_exp_f32_e32 v15, v15
	v_exp_f32_e32 v56, v48
	v_cvt_pk_bf16_f32 v48, v1, v2
	v_add_f32_e32 v0, v11, v0
	v_sub_f32_e32 v1, v64, v129
	v_add_f32_e32 v0, v12, v0
	v_mul_f32_e32 v1, 0x3fb8aa3b, v1
	v_sub_f32_e32 v2, v65, v129
	v_cvt_pk_bf16_f32 v49, v3, v4
	v_add_f32_e32 v0, v13, v0
	v_exp_f32_e32 v1, v1
	v_mul_f32_e32 v2, 0x3fb8aa3b, v2
	v_sub_f32_e32 v3, v66, v129
	v_add_f32_e32 v0, v14, v0
	v_exp_f32_e32 v2, v2
	v_mul_f32_e32 v3, 0x3fb8aa3b, v3
	v_sub_f32_e32 v4, v67, v129
	v_cvt_pk_bf16_f32 v50, v5, v6
	v_add_f32_e32 v0, v15, v0
	v_exp_f32_e32 v3, v3
	v_mul_f32_e32 v4, 0x3fb8aa3b, v4
	v_sub_f32_e32 v5, v68, v129
	v_add_f32_e32 v0, v56, v0
	v_exp_f32_e32 v4, v4
	v_mul_f32_e32 v5, 0x3fb8aa3b, v5
	v_sub_f32_e32 v6, v69, v129
	v_cvt_pk_bf16_f32 v51, v7, v8
	v_exp_f32_e32 v5, v5
	v_mul_f32_e32 v6, 0x3fb8aa3b, v6
	v_sub_f32_e32 v7, v70, v129
	v_add_f32_e32 v0, v1, v0
	v_exp_f32_e32 v6, v6
	v_mul_f32_e32 v7, 0x3fb8aa3b, v7
	v_sub_f32_e32 v8, v71, v129
	v_add_f32_e32 v0, v2, v0
	v_cvt_pk_bf16_f32 v52, v9, v10
	v_exp_f32_e32 v7, v7
	v_mul_f32_e32 v8, 0x3fb8aa3b, v8
	v_sub_f32_e32 v9, v72, v129
	v_add_f32_e32 v0, v3, v0
	v_exp_f32_e32 v8, v8
	v_mul_f32_e32 v9, 0x3fb8aa3b, v9
	v_sub_f32_e32 v10, v73, v129
	v_add_f32_e32 v0, v4, v0
	v_cvt_pk_bf16_f32 v53, v11, v12
	v_exp_f32_e32 v9, v9
	v_mul_f32_e32 v10, 0x3fb8aa3b, v10
	v_sub_f32_e32 v11, v74, v129
	v_add_f32_e32 v0, v5, v0
	v_exp_f32_e32 v10, v10
	v_mul_f32_e32 v11, 0x3fb8aa3b, v11
	v_sub_f32_e32 v12, v75, v129
	v_add_f32_e32 v0, v6, v0
	v_cvt_pk_bf16_f32 v54, v13, v14
	v_exp_f32_e32 v11, v11
	v_mul_f32_e32 v12, 0x3fb8aa3b, v12
	v_sub_f32_e32 v13, v76, v129
	v_add_f32_e32 v0, v7, v0
	v_exp_f32_e32 v12, v12
	v_mul_f32_e32 v13, 0x3fb8aa3b, v13
	v_sub_f32_e32 v14, v77, v129
	v_add_f32_e32 v0, v8, v0
	v_cvt_pk_bf16_f32 v55, v15, v56
	v_exp_f32_e32 v13, v13
	v_mul_f32_e32 v14, 0x3fb8aa3b, v14
	v_sub_f32_e32 v15, v78, v129
	v_sub_f32_e32 v56, v79, v129
	v_add_f32_e32 v0, v9, v0
	v_exp_f32_e32 v14, v14
	v_mul_f32_e32 v15, 0x3fb8aa3b, v15
	v_mul_f32_e32 v56, 0x3fb8aa3b, v56
	v_add_f32_e32 v0, v10, v0
	v_exp_f32_e32 v15, v15
	v_exp_f32_e32 v64, v56
	v_cvt_pk_bf16_f32 v56, v1, v2
	v_add_f32_e32 v0, v11, v0
	v_sub_f32_e32 v1, v112, v129
	v_add_f32_e32 v0, v12, v0
	v_mul_f32_e32 v1, 0x3fb8aa3b, v1
	v_sub_f32_e32 v2, v113, v129
	v_cvt_pk_bf16_f32 v57, v3, v4
	v_add_f32_e32 v0, v13, v0
	v_exp_f32_e32 v1, v1
	v_mul_f32_e32 v2, 0x3fb8aa3b, v2
	v_sub_f32_e32 v3, v114, v129
	v_add_f32_e32 v0, v14, v0
	v_exp_f32_e32 v2, v2
	v_mul_f32_e32 v3, 0x3fb8aa3b, v3
	v_sub_f32_e32 v4, v115, v129
	v_cvt_pk_bf16_f32 v58, v5, v6
	v_add_f32_e32 v0, v15, v0
	v_exp_f32_e32 v3, v3
	v_mul_f32_e32 v4, 0x3fb8aa3b, v4
	v_sub_f32_e32 v5, v116, v129
	v_add_f32_e32 v0, v64, v0
	v_exp_f32_e32 v4, v4
	v_mul_f32_e32 v5, 0x3fb8aa3b, v5
	v_sub_f32_e32 v6, v117, v129
	v_cvt_pk_bf16_f32 v59, v7, v8
	v_exp_f32_e32 v5, v5
	v_mul_f32_e32 v6, 0x3fb8aa3b, v6
	v_sub_f32_e32 v7, v118, v129
	v_add_f32_e32 v0, v1, v0
	v_exp_f32_e32 v6, v6
	v_mul_f32_e32 v7, 0x3fb8aa3b, v7
	v_sub_f32_e32 v8, v119, v129
	v_add_f32_e32 v0, v2, v0
	v_cvt_pk_bf16_f32 v60, v9, v10
	v_exp_f32_e32 v7, v7
	v_mul_f32_e32 v8, 0x3fb8aa3b, v8
	v_sub_f32_e32 v9, v120, v129
	v_add_f32_e32 v0, v3, v0
	v_exp_f32_e32 v8, v8
	v_mul_f32_e32 v9, 0x3fb8aa3b, v9
	v_sub_f32_e32 v10, v121, v129
	v_add_f32_e32 v0, v4, v0
	v_cvt_pk_bf16_f32 v61, v11, v12
	v_exp_f32_e32 v9, v9
	v_mul_f32_e32 v10, 0x3fb8aa3b, v10
	v_sub_f32_e32 v11, v122, v129
	v_add_f32_e32 v0, v5, v0
	v_exp_f32_e32 v10, v10
	v_mul_f32_e32 v11, 0x3fb8aa3b, v11
	v_sub_f32_e32 v12, v123, v129
	v_add_f32_e32 v0, v6, v0
	v_cvt_pk_bf16_f32 v62, v13, v14
	v_exp_f32_e32 v11, v11
	v_mul_f32_e32 v12, 0x3fb8aa3b, v12
	v_sub_f32_e32 v13, v124, v129
	v_add_f32_e32 v0, v7, v0
	v_exp_f32_e32 v12, v12
	v_mul_f32_e32 v13, 0x3fb8aa3b, v13
	v_sub_f32_e32 v14, v125, v129
	v_add_f32_e32 v0, v8, v0
	v_cvt_pk_bf16_f32 v63, v15, v64
	v_exp_f32_e32 v13, v13
	v_mul_f32_e32 v14, 0x3fb8aa3b, v14
	v_sub_f32_e32 v15, v126, v129
	v_add_f32_e32 v0, v9, v0
	v_exp_f32_e32 v14, v14
	v_mul_f32_e32 v15, 0x3fb8aa3b, v15
	v_sub_f32_e32 v64, v127, v129
	v_add_f32_e32 v0, v10, v0
	v_exp_f32_e32 v15, v15
	v_mul_f32_e32 v64, 0x3fb8aa3b, v64
	v_add_f32_e32 v0, v11, v0
	v_exp_f32_e32 v72, v64
	v_add_f32_e32 v0, v12, v0
	v_add_f32_e32 v0, v13, v0
	v_add_f32_e32 v0, v14, v0
	v_add_f32_e32 v0, v15, v0
	v_add_f32_e32 v0, v72, v0
	v_cvt_pk_bf16_f32 v64, v1, v2
	ds_bpermute_b32 v1, v128, v0
	v_cvt_pk_bf16_f32 v65, v3, v4
	v_cvt_pk_bf16_f32 v66, v5, v6
	v_cvt_pk_bf16_f32 v71, v15, v72
	v_cvt_pk_bf16_f32 v97, v132, v133
	s_waitcnt lgkmcnt(0)
	v_add_f32_e32 v0, v0, v1
	v_div_scale_f32 v1, s[14:15], v0, v0, 1.0
	v_rcp_f32_e32 v2, v1
	v_cvt_pk_bf16_f32 v98, v134, v135
	v_cvt_pk_bf16_f32 v99, v136, v137
	v_cvt_pk_bf16_f32 v32, v105, v106
	v_fma_f32 v3, -v1, v2, 1.0
	v_fmac_f32_e32 v2, v3, v2
	v_div_scale_f32 v3, vcc, 1.0, v0, 1.0
	v_mul_f32_e32 v4, v3, v2
	v_fma_f32 v5, -v1, v4, v3
	v_fmac_f32_e32 v4, v5, v2
	v_fma_f32 v1, -v1, v4, v3
	v_div_fmas_f32 v1, v1, v2, v4
	v_div_fixup_f32 v72, v1, v0, 1.0
	v_add_u32_e32 v0, s6, v214
	v_ashrrev_i32_e32 v1, 31, v0
	v_lshlrev_b64 v[0:1], 11, v[0:1]
	v_lshl_add_u64 v[2:3], s[48:49], 0, v[188:189]
	v_lshl_add_u64 v[0:1], v[0:1], 0, s[4:5]
	v_lshl_add_u64 v[0:1], v[2:3], 0, v[0:1]
	s_mov_b64 s[4:5], 0xc000020
	v_cvt_pk_bf16_f32 v33, v107, v108
	v_cvt_pk_bf16_f32 v34, v109, v110
	v_cvt_pk_bf16_f32 v35, v111, v130
	v_cvt_pk_bf16_f32 v67, v7, v8
	v_cvt_pk_bf16_f32 v68, v9, v10
	v_cvt_pk_bf16_f32 v69, v11, v12
	v_cvt_pk_bf16_f32 v70, v13, v14
	v_mov_b32_e32 v73, v72
	v_lshl_add_u64 v[74:75], v[0:1], 0, s[4:5]
	v_lshlrev_b32_e32 v76, 1, v211
	s_mov_b32 s4, 0
